# all GEMM main loops: first 8 MFMAs of each compute segment issued before the segment's opening barrier (operands already waited on)
# baseline (speedup 1.0000x reference)
.LBB0_198:
	ds_read_b128 v[18:21], v176
	ds_read_b128 v[22:25], v176 offset:1024
	ds_read_b128 v[34:37], v176 offset:2048
	ds_read_b128 v[38:41], v176 offset:3072
	ds_read_b128 v[164:167], v177
	ds_read_b128 v[168:171], v177 offset:1024
	ds_read_b128 v[180:183], v177 offset:2048
	ds_read_b128 v[184:187], v177 offset:3072
	s_add_u32 s8, s0, 0xfffc0080
	s_addc_u32 s9, s1, -1
	s_cmp_eq_u32 s96, 12
	s_cselect_b32 s11, s7, s9
	s_cselect_b32 s10, s40, s8
	s_cselect_b32 s9, s41, s93
	s_cselect_b32 s8, s65, s67
	v_lshl_add_u64 v[172:173], s[0:1], 0, v[156:157]
	s_add_i32 m0, s21, 0xc000
	ds_read_b128 v[188:191], v178
	ds_read_b128 v[192:195], v178 offset:1024
	ds_read_b128 v[196:199], v178 offset:2048
	ds_read_b128 v[200:203], v178 offset:3072
	ds_read_b128 v[204:207], v178 offset:4096
	ds_read_b128 v[208:211], v178 offset:5120
	ds_read_b128 v[212:215], v178 offset:6144
	ds_read_b128 v[220:223], v178 offset:7168
	global_load_lds_dwordx4 v[172:173], off
	v_lshl_add_u64 v[172:173], s[0:1], 0, v[158:159]
	s_add_i32 m0, s21, 0xe000
	s_nop 0
	global_load_lds_dwordx4 v[172:173], off
	s_waitcnt vmcnt(8)
	s_waitcnt lgkmcnt(0)
	v_mfma_f32_16x16x32_bf16 v[142:145], v[18:21], v[188:191], v[142:145]
	v_mfma_f32_16x16x32_bf16 v[138:141], v[34:37], v[188:191], v[138:141]
	v_mfma_f32_16x16x32_bf16 v[126:129], v[18:21], v[196:199], v[126:129]
	v_mfma_f32_16x16x32_bf16 v[122:125], v[34:37], v[196:199], v[122:125]
	v_mfma_f32_16x16x32_bf16 v[110:113], v[18:21], v[204:207], v[110:113]
	v_mfma_f32_16x16x32_bf16 v[106:109], v[34:37], v[204:207], v[106:109]
	v_mfma_f32_16x16x32_bf16 v[94:97], v[18:21], v[212:215], v[94:97]
	v_mfma_f32_16x16x32_bf16 v[90:93], v[34:37], v[212:215], v[90:93]
	s_barrier
	s_setprio 1
	s_waitcnt lgkmcnt(0)
	v_mfma_f32_16x16x32_bf16 v[142:145], v[22:25], v[192:195], v[142:145]
	v_mfma_f32_16x16x32_bf16 v[138:141], v[38:41], v[192:195], v[138:141]
	v_mfma_f32_16x16x32_bf16 v[126:129], v[22:25], v[200:203], v[126:129]
	v_mfma_f32_16x16x32_bf16 v[122:125], v[38:41], v[200:203], v[122:125]
	v_mfma_f32_16x16x32_bf16 v[110:113], v[22:25], v[208:211], v[110:113]
	v_mfma_f32_16x16x32_bf16 v[106:109], v[38:41], v[208:211], v[106:109]
	v_mfma_f32_16x16x32_bf16 v[94:97], v[22:25], v[220:223], v[94:97]
	v_mfma_f32_16x16x32_bf16 v[90:93], v[38:41], v[220:223], v[90:93]
	s_setprio 0
	s_setprio 1
	v_mfma_f32_16x16x32_bf16 v[134:137], v[164:167], v[188:191], v[134:137]
	v_mfma_f32_16x16x32_bf16 v[130:133], v[180:183], v[188:191], v[130:133]
	v_mfma_f32_16x16x32_bf16 v[118:121], v[164:167], v[196:199], v[118:121]
	v_mfma_f32_16x16x32_bf16 v[114:117], v[180:183], v[196:199], v[114:117]
	v_mfma_f32_16x16x32_bf16 v[102:105], v[164:167], v[204:207], v[102:105]
	v_mfma_f32_16x16x32_bf16 v[98:101], v[180:183], v[204:207], v[98:101]
	v_mfma_f32_16x16x32_bf16 v[86:89], v[164:167], v[212:215], v[86:89]
	v_mfma_f32_16x16x32_bf16 v[82:85], v[180:183], v[212:215], v[82:85]
	v_mfma_f32_16x16x32_bf16 v[134:137], v[168:171], v[192:195], v[134:137]
	v_mfma_f32_16x16x32_bf16 v[130:133], v[184:187], v[192:195], v[130:133]
	v_mfma_f32_16x16x32_bf16 v[118:121], v[168:171], v[200:203], v[118:121]
	v_mfma_f32_16x16x32_bf16 v[114:117], v[184:187], v[200:203], v[114:117]
	v_mfma_f32_16x16x32_bf16 v[102:105], v[168:171], v[208:211], v[102:105]
	v_mfma_f32_16x16x32_bf16 v[98:101], v[184:187], v[208:211], v[98:101]
	v_mfma_f32_16x16x32_bf16 v[86:89], v[168:171], v[220:223], v[86:89]
	v_mfma_f32_16x16x32_bf16 v[82:85], v[184:187], v[220:223], v[82:85]
	s_setprio 0
	s_barrier
	s_add_i32 s97, s45, s35
	v_lshl_add_u64 v[172:173], s[8:9], 0, v[148:149]
	s_mov_b32 m0, s97
	ds_read_b128 v[188:191], v178 offset:16384
	ds_read_b128 v[192:195], v178 offset:17408
	ds_read_b128 v[196:199], v178 offset:18432
	ds_read_b128 v[200:203], v178 offset:19456
	ds_read_b128 v[204:207], v178 offset:20480
	ds_read_b128 v[208:211], v178 offset:21504
	ds_read_b128 v[212:215], v178 offset:22528
	ds_read_b128 v[220:223], v178 offset:23552
	global_load_lds_dwordx4 v[172:173], off
	s_add_i32 m0, s97, 0x2000
	s_add_u32 vcc_lo, s8, 0x40000
	v_lshl_add_u64 v[216:217], s[8:9], 0, v[152:153]
	s_addc_u32 vcc_hi, s9, 0
	s_add_i32 s97, s92, s35
	global_load_lds_dwordx4 v[216:217], off
	v_lshl_add_u64 v[224:225], vcc, 0, v[148:149]
	s_mov_b32 m0, s97
	v_lshl_add_u64 v[226:227], s[10:11], 0, v[150:151]
	global_load_lds_dwordx4 v[224:225], off
	v_lshl_add_u64 v[224:225], vcc, 0, v[152:153]
	s_add_i32 m0, s97, 0x2000
	s_nop 0
	global_load_lds_dwordx4 v[224:225], off
	v_lshl_add_u64 v[224:225], s[10:11], 0, v[146:147]
	s_mov_b32 m0, s21
	s_nop 0
	global_load_lds_dwordx4 v[224:225], off
	s_mov_b32 m0, s37
	s_nop 0
	global_load_lds_dwordx4 v[226:227], off
	s_waitcnt vmcnt(8)
	s_waitcnt lgkmcnt(0)
	v_mfma_f32_16x16x32_bf16 v[78:81], v[18:21], v[188:191], v[78:81]
	v_mfma_f32_16x16x32_bf16 v[74:77], v[34:37], v[188:191], v[74:77]
	v_mfma_f32_16x16x32_bf16 v[62:65], v[18:21], v[196:199], v[62:65]
	v_mfma_f32_16x16x32_bf16 v[58:61], v[34:37], v[196:199], v[58:61]
	v_mfma_f32_16x16x32_bf16 v[46:49], v[18:21], v[204:207], v[46:49]
	v_mfma_f32_16x16x32_bf16 v[42:45], v[34:37], v[204:207], v[42:45]
	v_mfma_f32_16x16x32_bf16 v[14:17], v[18:21], v[212:215], v[14:17]
	v_mfma_f32_16x16x32_bf16 v[10:13], v[34:37], v[212:215], v[10:13]
	s_barrier
	s_setprio 1
	s_waitcnt lgkmcnt(0)
	v_mfma_f32_16x16x32_bf16 v[78:81], v[22:25], v[192:195], v[78:81]
	v_mfma_f32_16x16x32_bf16 v[74:77], v[38:41], v[192:195], v[74:77]
	v_mfma_f32_16x16x32_bf16 v[62:65], v[22:25], v[200:203], v[62:65]
	v_mfma_f32_16x16x32_bf16 v[58:61], v[38:41], v[200:203], v[58:61]
	v_mfma_f32_16x16x32_bf16 v[46:49], v[22:25], v[208:211], v[46:49]
	v_mfma_f32_16x16x32_bf16 v[42:45], v[38:41], v[208:211], v[42:45]
	v_mfma_f32_16x16x32_bf16 v[14:17], v[22:25], v[220:223], v[14:17]
	v_mfma_f32_16x16x32_bf16 v[10:13], v[38:41], v[220:223], v[10:13]
	s_setprio 0
	s_setprio 1
	v_mfma_f32_16x16x32_bf16 v[30:33], v[164:167], v[204:207], v[30:33]
	v_mfma_f32_16x16x32_bf16 v[26:29], v[180:183], v[204:207], v[26:29]
	v_mfma_f32_16x16x32_bf16 v[6:9], v[164:167], v[212:215], v[6:9]
	v_mfma_f32_16x16x32_bf16 v[2:5], v[180:183], v[212:215], v[2:5]
	v_mfma_f32_16x16x32_bf16 v[18:21], v[164:167], v[188:191], v[70:73]
	v_mfma_f32_16x16x32_bf16 v[22:25], v[180:183], v[188:191], v[66:69]
	v_mfma_f32_16x16x32_bf16 v[34:37], v[164:167], v[196:199], v[54:57]
	v_mfma_f32_16x16x32_bf16 v[38:41], v[180:183], v[196:199], v[50:53]
	v_mfma_f32_16x16x32_bf16 v[30:33], v[168:171], v[208:211], v[30:33]
	v_mfma_f32_16x16x32_bf16 v[26:29], v[184:187], v[208:211], v[26:29]
	v_mfma_f32_16x16x32_bf16 v[6:9], v[168:171], v[220:223], v[6:9]
	v_mfma_f32_16x16x32_bf16 v[2:5], v[184:187], v[220:223], v[2:5]
	v_mfma_f32_16x16x32_bf16 v[18:21], v[168:171], v[192:195], v[18:21]
	v_mfma_f32_16x16x32_bf16 v[22:25], v[184:187], v[192:195], v[22:25]
	v_mfma_f32_16x16x32_bf16 v[34:37], v[168:171], v[200:203], v[34:37]
	v_mfma_f32_16x16x32_bf16 v[38:41], v[184:187], v[200:203], v[38:41]
	s_setprio 0
	s_barrier
	s_add_i32 s97, 0, 0x18000
	s_add_i32 vcc_lo, 0, 0x1c000
	v_add_u32_e32 v70, s97, v174
	v_add_u32_e32 v155, vcc_lo, v174
	ds_read_b128 v[50:53], v70
	ds_read_b128 v[54:57], v70 offset:1024
	ds_read_b128 v[66:69], v70 offset:2048
	ds_read_b128 v[70:73], v70 offset:3072
	ds_read_b128 v[164:167], v155
	ds_read_b128 v[168:171], v155 offset:1024
	ds_read_b128 v[180:183], v155 offset:2048
	ds_read_b128 v[184:187], v155 offset:3072
	s_add_u32 s10, s10, 0x40000
	s_addc_u32 s11, s11, 0
	s_mov_b32 m0, s39
	v_lshl_add_u64 v[228:229], s[10:11], 0, v[146:147]
	ds_read_b128 v[188:191], v178 offset:32768
	ds_read_b128 v[192:195], v178 offset:33792
	ds_read_b128 v[196:199], v178 offset:34816
	ds_read_b128 v[200:203], v178 offset:35840
	ds_read_b128 v[204:207], v178 offset:36864
	ds_read_b128 v[208:211], v178 offset:37888
	ds_read_b128 v[212:215], v178 offset:38912
	ds_read_b128 v[220:223], v178 offset:39936
	global_load_lds_dwordx4 v[228:229], off
	v_lshl_add_u64 v[228:229], s[10:11], 0, v[150:151]
	s_mov_b32 m0, s51
	s_nop 0
	global_load_lds_dwordx4 v[228:229], off
	s_waitcnt vmcnt(8)
	s_waitcnt lgkmcnt(0)
	v_mfma_f32_16x16x32_bf16 v[142:145], v[50:53], v[188:191], v[142:145]
	v_mfma_f32_16x16x32_bf16 v[138:141], v[66:69], v[188:191], v[138:141]
	v_mfma_f32_16x16x32_bf16 v[126:129], v[50:53], v[196:199], v[126:129]
	v_mfma_f32_16x16x32_bf16 v[122:125], v[66:69], v[196:199], v[122:125]
	v_mfma_f32_16x16x32_bf16 v[110:113], v[50:53], v[204:207], v[110:113]
	v_mfma_f32_16x16x32_bf16 v[106:109], v[66:69], v[204:207], v[106:109]
	v_mfma_f32_16x16x32_bf16 v[94:97], v[50:53], v[212:215], v[94:97]
	v_mfma_f32_16x16x32_bf16 v[90:93], v[66:69], v[212:215], v[90:93]
	s_barrier
	s_setprio 1
	s_waitcnt lgkmcnt(0)
	v_mfma_f32_16x16x32_bf16 v[142:145], v[54:57], v[192:195], v[142:145]
	v_mfma_f32_16x16x32_bf16 v[138:141], v[70:73], v[192:195], v[138:141]
	v_mfma_f32_16x16x32_bf16 v[126:129], v[54:57], v[200:203], v[126:129]
	v_mfma_f32_16x16x32_bf16 v[122:125], v[70:73], v[200:203], v[122:125]
	v_mfma_f32_16x16x32_bf16 v[110:113], v[54:57], v[208:211], v[110:113]
	v_mfma_f32_16x16x32_bf16 v[106:109], v[70:73], v[208:211], v[106:109]
	v_mfma_f32_16x16x32_bf16 v[94:97], v[54:57], v[220:223], v[94:97]
	v_mfma_f32_16x16x32_bf16 v[90:93], v[70:73], v[220:223], v[90:93]
	s_setprio 0
	s_setprio 1
	v_mfma_f32_16x16x32_bf16 v[134:137], v[164:167], v[188:191], v[134:137]
	v_mfma_f32_16x16x32_bf16 v[130:133], v[180:183], v[188:191], v[130:133]
	v_mfma_f32_16x16x32_bf16 v[118:121], v[164:167], v[196:199], v[118:121]
	v_mfma_f32_16x16x32_bf16 v[114:117], v[180:183], v[196:199], v[114:117]
	v_mfma_f32_16x16x32_bf16 v[102:105], v[164:167], v[204:207], v[102:105]
	v_mfma_f32_16x16x32_bf16 v[98:101], v[180:183], v[204:207], v[98:101]
	v_mfma_f32_16x16x32_bf16 v[86:89], v[164:167], v[212:215], v[86:89]
	v_mfma_f32_16x16x32_bf16 v[82:85], v[180:183], v[212:215], v[82:85]
	v_mfma_f32_16x16x32_bf16 v[134:137], v[168:171], v[192:195], v[134:137]
	v_mfma_f32_16x16x32_bf16 v[130:133], v[184:187], v[192:195], v[130:133]
	v_mfma_f32_16x16x32_bf16 v[118:121], v[168:171], v[200:203], v[118:121]
	v_mfma_f32_16x16x32_bf16 v[114:117], v[184:187], v[200:203], v[114:117]
	v_mfma_f32_16x16x32_bf16 v[102:105], v[168:171], v[208:211], v[102:105]
	v_mfma_f32_16x16x32_bf16 v[98:101], v[184:187], v[208:211], v[98:101]
	v_mfma_f32_16x16x32_bf16 v[86:89], v[168:171], v[220:223], v[86:89]
	v_mfma_f32_16x16x32_bf16 v[82:85], v[184:187], v[220:223], v[82:85]
	s_setprio 0
	s_barrier
	s_add_i32 s10, s97, s35
	v_lshl_add_u64 v[172:173], v[172:173], 0, s[28:29]
	s_mov_b32 m0, s10
	ds_read_b128 v[188:191], v178 offset:49152
	ds_read_b128 v[192:195], v178 offset:50176
	ds_read_b128 v[196:199], v178 offset:51200
	ds_read_b128 v[200:203], v178 offset:52224
	ds_read_b128 v[204:207], v178 offset:53248
	ds_read_b128 v[208:211], v178 offset:54272
	ds_read_b128 v[212:215], v178 offset:55296
	ds_read_b128 v[220:223], v178 offset:56320
	global_load_lds_dwordx4 v[172:173], off
	s_add_i32 m0, s10, 0x2000
	s_add_u32 s8, s8, 0x40080
	v_lshl_add_u64 v[172:173], v[216:217], 0, s[28:29]
	s_addc_u32 s9, s9, 0
	s_add_i32 s10, vcc_lo, s35
	global_load_lds_dwordx4 v[172:173], off
	v_lshl_add_u64 v[172:173], s[8:9], 0, v[148:149]
	s_mov_b32 m0, s10
	s_nop 0
	global_load_lds_dwordx4 v[172:173], off
	v_lshl_add_u64 v[172:173], s[8:9], 0, v[152:153]
	s_add_i32 m0, s10, 0x2000
	s_nop 0
	global_load_lds_dwordx4 v[172:173], off
	v_lshl_add_u64 v[172:173], v[224:225], 0, s[28:29]
	s_mov_b32 m0, s57
	s_nop 0
	global_load_lds_dwordx4 v[172:173], off
	v_lshl_add_u64 v[172:173], v[226:227], 0, s[28:29]
	s_mov_b32 m0, s59
	s_nop 0
	global_load_lds_dwordx4 v[172:173], off
	s_waitcnt vmcnt(8)
	s_waitcnt lgkmcnt(0)
	v_mfma_f32_16x16x32_bf16 v[78:81], v[50:53], v[188:191], v[78:81]
	v_mfma_f32_16x16x32_bf16 v[74:77], v[66:69], v[188:191], v[74:77]
	v_mfma_f32_16x16x32_bf16 v[62:65], v[50:53], v[196:199], v[62:65]
	v_mfma_f32_16x16x32_bf16 v[58:61], v[66:69], v[196:199], v[58:61]
	v_mfma_f32_16x16x32_bf16 v[46:49], v[50:53], v[204:207], v[46:49]
	v_mfma_f32_16x16x32_bf16 v[42:45], v[66:69], v[204:207], v[42:45]
	v_mfma_f32_16x16x32_bf16 v[14:17], v[50:53], v[212:215], v[14:17]
	v_mfma_f32_16x16x32_bf16 v[10:13], v[66:69], v[212:215], v[10:13]
	s_barrier
	s_setprio 1
	s_waitcnt lgkmcnt(0)
	v_mfma_f32_16x16x32_bf16 v[78:81], v[54:57], v[192:195], v[78:81]
	v_mfma_f32_16x16x32_bf16 v[74:77], v[70:73], v[192:195], v[74:77]
	v_mfma_f32_16x16x32_bf16 v[62:65], v[54:57], v[200:203], v[62:65]
	v_mfma_f32_16x16x32_bf16 v[58:61], v[70:73], v[200:203], v[58:61]
	v_mfma_f32_16x16x32_bf16 v[46:49], v[54:57], v[208:211], v[46:49]
	v_mfma_f32_16x16x32_bf16 v[42:45], v[70:73], v[208:211], v[42:45]
	v_mfma_f32_16x16x32_bf16 v[14:17], v[54:57], v[220:223], v[14:17]
	v_mfma_f32_16x16x32_bf16 v[10:13], v[70:73], v[220:223], v[10:13]
	s_setprio 0
	s_setprio 1
	v_mfma_f32_16x16x32_bf16 v[18:21], v[164:167], v[188:191], v[18:21]
	v_mfma_f32_16x16x32_bf16 v[70:73], v[168:171], v[192:195], v[18:21]
	v_mfma_f32_16x16x32_bf16 v[18:21], v[180:183], v[188:191], v[22:25]
	v_mfma_f32_16x16x32_bf16 v[66:69], v[184:187], v[192:195], v[18:21]
	v_mfma_f32_16x16x32_bf16 v[18:21], v[164:167], v[196:199], v[34:37]
	v_mfma_f32_16x16x32_bf16 v[54:57], v[168:171], v[200:203], v[18:21]
	v_mfma_f32_16x16x32_bf16 v[18:21], v[180:183], v[196:199], v[38:41]
	v_mfma_f32_16x16x32_bf16 v[50:53], v[184:187], v[200:203], v[18:21]
	v_mfma_f32_16x16x32_bf16 v[18:21], v[164:167], v[204:207], v[30:33]
	v_mfma_f32_16x16x32_bf16 v[30:33], v[168:171], v[208:211], v[18:21]
	v_mfma_f32_16x16x32_bf16 v[18:21], v[180:183], v[204:207], v[26:29]
	v_mfma_f32_16x16x32_bf16 v[6:9], v[164:167], v[212:215], v[6:9]
	v_mfma_f32_16x16x32_bf16 v[2:5], v[180:183], v[212:215], v[2:5]
	v_mfma_f32_16x16x32_bf16 v[26:29], v[184:187], v[208:211], v[18:21]
	v_mfma_f32_16x16x32_bf16 v[6:9], v[168:171], v[220:223], v[6:9]
	v_mfma_f32_16x16x32_bf16 v[2:5], v[184:187], v[220:223], v[2:5]
	s_setprio 0
	s_barrier
	s_add_i32 s96, s96, 2
	s_add_u32 s0, s0, 0x100
	s_addc_u32 s1, s1, 0
	s_add_u32 s67, s67, 0x100
	s_addc_u32 s93, s93, 0
	s_cmp_gt_u32 s96, 13
	s_cbranch_scc0 .LBB0_198
	s_and_b64 vcc, exec, s[30:31]
	s_cbranch_vccz .LBB0_201
	s_barrier

.LBB0_772:
	v_add_u32_e32 v3, s35, v164
	ds_read_b128 v[134:137], v3
	ds_read_b128 v[138:141], v3 offset:1024
	ds_read_b128 v[158:161], v3 offset:2048
	ds_read_b128 v[168:171], v3 offset:3072
	v_add_u32_e32 v3, s36, v164
	ds_read_b128 v[172:175], v3
	ds_read_b128 v[176:179], v3 offset:1024
	ds_read_b128 v[180:183], v3 offset:2048
	ds_read_b128 v[184:187], v3 offset:3072
	s_add_u32 s20, s18, 0xfffc0080
	s_addc_u32 s21, s19, -1
	s_cmp_eq_u32 s54, 12
	s_cselect_b32 s45, s11, s21
	s_cselect_b32 s44, s39, s20
	s_cselect_b32 s21, s9, s53
	s_cselect_b32 s20, s51, s52
	v_lshl_add_u64 v[4:5], s[18:19], 0, v[150:151]
	s_add_i32 m0, s25, 0xc000
	ds_read_b128 v[188:191], v166
	ds_read_b128 v[192:195], v166 offset:1024
	ds_read_b128 v[196:199], v166 offset:2048
	ds_read_b128 v[200:203], v166 offset:3072
	ds_read_b128 v[204:207], v166 offset:4096
	ds_read_b128 v[208:211], v166 offset:5120
	ds_read_b128 v[212:215], v166 offset:6144
	ds_read_b128 v[220:223], v166 offset:7168
	global_load_lds_dwordx4 v[4:5], off
	v_lshl_add_u64 v[4:5], s[18:19], 0, v[152:153]
	s_add_i32 m0, s25, 0xe000
	s_nop 0
	global_load_lds_dwordx4 v[4:5], off
	s_waitcnt vmcnt(8)
	s_waitcnt lgkmcnt(0)
	v_mfma_f32_16x16x32_bf16 v[130:133], v[134:137], v[188:191], v[130:133]
	v_mfma_f32_16x16x32_bf16 v[126:129], v[158:161], v[188:191], v[126:129]
	v_mfma_f32_16x16x32_bf16 v[122:125], v[134:137], v[196:199], v[122:125]
	v_mfma_f32_16x16x32_bf16 v[118:121], v[158:161], v[196:199], v[118:121]
	v_mfma_f32_16x16x32_bf16 v[114:117], v[134:137], v[204:207], v[114:117]
	v_mfma_f32_16x16x32_bf16 v[110:113], v[158:161], v[204:207], v[110:113]
	v_mfma_f32_16x16x32_bf16 v[106:109], v[134:137], v[212:215], v[106:109]
	v_mfma_f32_16x16x32_bf16 v[102:105], v[158:161], v[212:215], v[102:105]
	s_barrier
	s_setprio 1
	s_waitcnt lgkmcnt(0)
	v_mfma_f32_16x16x32_bf16 v[130:133], v[138:141], v[192:195], v[130:133]
	v_mfma_f32_16x16x32_bf16 v[126:129], v[168:171], v[192:195], v[126:129]
	v_mfma_f32_16x16x32_bf16 v[122:125], v[138:141], v[200:203], v[122:125]
	v_mfma_f32_16x16x32_bf16 v[118:121], v[168:171], v[200:203], v[118:121]
	v_mfma_f32_16x16x32_bf16 v[114:117], v[138:141], v[208:211], v[114:117]
	v_mfma_f32_16x16x32_bf16 v[110:113], v[168:171], v[208:211], v[110:113]
	v_mfma_f32_16x16x32_bf16 v[106:109], v[138:141], v[220:223], v[106:109]
	v_mfma_f32_16x16x32_bf16 v[102:105], v[168:171], v[220:223], v[102:105]
	s_setprio 0
	s_setprio 1
	v_mfma_f32_16x16x32_bf16 v[98:101], v[172:175], v[188:191], v[98:101]
	v_mfma_f32_16x16x32_bf16 v[94:97], v[180:183], v[188:191], v[94:97]
	v_mfma_f32_16x16x32_bf16 v[90:93], v[172:175], v[196:199], v[90:93]
	v_mfma_f32_16x16x32_bf16 v[86:89], v[180:183], v[196:199], v[86:89]
	v_mfma_f32_16x16x32_bf16 v[82:85], v[172:175], v[204:207], v[82:85]
	v_mfma_f32_16x16x32_bf16 v[78:81], v[180:183], v[204:207], v[78:81]
	v_mfma_f32_16x16x32_bf16 v[74:77], v[172:175], v[212:215], v[74:77]
	v_mfma_f32_16x16x32_bf16 v[70:73], v[180:183], v[212:215], v[70:73]
	v_mfma_f32_16x16x32_bf16 v[98:101], v[176:179], v[192:195], v[98:101]
	v_mfma_f32_16x16x32_bf16 v[94:97], v[184:187], v[192:195], v[94:97]
	v_mfma_f32_16x16x32_bf16 v[90:93], v[176:179], v[200:203], v[90:93]
	v_mfma_f32_16x16x32_bf16 v[86:89], v[184:187], v[200:203], v[86:89]
	v_mfma_f32_16x16x32_bf16 v[82:85], v[176:179], v[208:211], v[82:85]
	v_mfma_f32_16x16x32_bf16 v[78:81], v[184:187], v[208:211], v[78:81]
	v_mfma_f32_16x16x32_bf16 v[74:77], v[176:179], v[220:223], v[74:77]
	v_mfma_f32_16x16x32_bf16 v[70:73], v[184:187], v[220:223], v[70:73]
	s_setprio 0
	s_barrier
	s_add_i32 s55, s35, s24
	v_lshl_add_u64 v[162:163], s[20:21], 0, v[146:147]
	s_mov_b32 m0, s55
	ds_read_b128 v[188:191], v166 offset:16384
	ds_read_b128 v[192:195], v166 offset:17408
	ds_read_b128 v[196:199], v166 offset:18432
	ds_read_b128 v[200:203], v166 offset:19456
	ds_read_b128 v[204:207], v166 offset:20480
	ds_read_b128 v[208:211], v166 offset:21504
	ds_read_b128 v[212:215], v166 offset:22528
	ds_read_b128 v[220:223], v166 offset:23552
	global_load_lds_dwordx4 v[162:163], off
	s_add_i32 m0, s55, 0x2000
	s_add_u32 s56, s20, 0x40000
	v_lshl_add_u64 v[216:217], s[20:21], 0, v[142:143]
	s_addc_u32 s57, s21, 0
	s_add_i32 s55, s36, s24
	global_load_lds_dwordx4 v[216:217], off
	v_lshl_add_u64 v[4:5], s[56:57], 0, v[146:147]
	s_mov_b32 m0, s55
	v_lshl_add_u64 v[224:225], s[44:45], 0, v[148:149]
	global_load_lds_dwordx4 v[4:5], off
	v_lshl_add_u64 v[4:5], s[56:57], 0, v[142:143]
	s_add_i32 m0, s55, 0x2000
	v_lshl_add_u64 v[226:227], s[44:45], 0, v[144:145]
	global_load_lds_dwordx4 v[4:5], off
	s_mov_b32 m0, s25
	s_nop 0
	global_load_lds_dwordx4 v[224:225], off
	s_mov_b32 m0, s26
	s_nop 0
	global_load_lds_dwordx4 v[226:227], off
	s_waitcnt vmcnt(8)
	s_waitcnt lgkmcnt(0)
	v_mfma_f32_16x16x32_bf16 v[66:69], v[134:137], v[188:191], v[66:69]
	v_mfma_f32_16x16x32_bf16 v[62:65], v[158:161], v[188:191], v[62:65]
	v_mfma_f32_16x16x32_bf16 v[58:61], v[134:137], v[196:199], v[58:61]
	v_mfma_f32_16x16x32_bf16 v[54:57], v[158:161], v[196:199], v[54:57]
	v_mfma_f32_16x16x32_bf16 v[50:53], v[134:137], v[204:207], v[50:53]
	v_mfma_f32_16x16x32_bf16 v[46:49], v[158:161], v[204:207], v[46:49]
	v_mfma_f32_16x16x32_bf16 v[42:45], v[134:137], v[212:215], v[42:45]
	v_mfma_f32_16x16x32_bf16 v[38:41], v[158:161], v[212:215], v[38:41]
	s_barrier
	s_setprio 1
	s_waitcnt lgkmcnt(0)
	v_mfma_f32_16x16x32_bf16 v[66:69], v[138:141], v[192:195], v[66:69]
	v_mfma_f32_16x16x32_bf16 v[62:65], v[168:171], v[192:195], v[62:65]
	v_mfma_f32_16x16x32_bf16 v[58:61], v[138:141], v[200:203], v[58:61]
	v_mfma_f32_16x16x32_bf16 v[54:57], v[168:171], v[200:203], v[54:57]
	v_mfma_f32_16x16x32_bf16 v[50:53], v[138:141], v[208:211], v[50:53]
	v_mfma_f32_16x16x32_bf16 v[46:49], v[168:171], v[208:211], v[46:49]
	v_mfma_f32_16x16x32_bf16 v[42:45], v[138:141], v[220:223], v[42:45]
	v_mfma_f32_16x16x32_bf16 v[38:41], v[168:171], v[220:223], v[38:41]
	s_setprio 0
	s_setprio 1
	v_mfma_f32_16x16x32_bf16 v[34:37], v[172:175], v[188:191], v[34:37]
	v_mfma_f32_16x16x32_bf16 v[30:33], v[180:183], v[188:191], v[30:33]
	v_mfma_f32_16x16x32_bf16 v[26:29], v[172:175], v[196:199], v[26:29]
	v_mfma_f32_16x16x32_bf16 v[22:25], v[180:183], v[196:199], v[22:25]
	v_mfma_f32_16x16x32_bf16 v[18:21], v[172:175], v[204:207], v[18:21]
	v_mfma_f32_16x16x32_bf16 v[14:17], v[180:183], v[204:207], v[14:17]
	v_mfma_f32_16x16x32_bf16 v[10:13], v[172:175], v[212:215], v[10:13]
	v_mfma_f32_16x16x32_bf16 v[4:7], v[180:183], v[212:215], v[6:9]
	v_mfma_f32_16x16x32_bf16 v[34:37], v[176:179], v[192:195], v[34:37]
	v_mfma_f32_16x16x32_bf16 v[30:33], v[184:187], v[192:195], v[30:33]
	v_mfma_f32_16x16x32_bf16 v[26:29], v[176:179], v[200:203], v[26:29]
	v_mfma_f32_16x16x32_bf16 v[22:25], v[184:187], v[200:203], v[22:25]
	v_mfma_f32_16x16x32_bf16 v[18:21], v[176:179], v[208:211], v[18:21]
	v_mfma_f32_16x16x32_bf16 v[14:17], v[184:187], v[208:211], v[14:17]
	v_mfma_f32_16x16x32_bf16 v[10:13], v[176:179], v[220:223], v[10:13]
	v_mfma_f32_16x16x32_bf16 v[4:7], v[184:187], v[220:223], v[4:7]
	s_setprio 0
	s_barrier
	s_add_i32 s55, 0, 0x18000
	v_add_u32_e32 v3, s55, v164
	s_add_i32 s56, 0, 0x1c000
	ds_read_b128 v[134:137], v3
	ds_read_b128 v[138:141], v3 offset:1024
	ds_read_b128 v[158:161], v3 offset:2048
	ds_read_b128 v[168:171], v3 offset:3072
	v_add_u32_e32 v3, s56, v164
	ds_read_b128 v[172:175], v3
	ds_read_b128 v[176:179], v3 offset:1024
	ds_read_b128 v[180:183], v3 offset:2048
	ds_read_b128 v[184:187], v3 offset:3072
	s_add_u32 s44, s44, 0x40000
	s_addc_u32 s45, s45, 0
	s_mov_b32 m0, s27
	v_lshl_add_u64 v[8:9], s[44:45], 0, v[148:149]
	ds_read_b128 v[188:191], v166 offset:32768
	ds_read_b128 v[192:195], v166 offset:33792
	ds_read_b128 v[196:199], v166 offset:34816
	ds_read_b128 v[200:203], v166 offset:35840
	ds_read_b128 v[204:207], v166 offset:36864
	ds_read_b128 v[208:211], v166 offset:37888
	ds_read_b128 v[212:215], v166 offset:38912
	ds_read_b128 v[220:223], v166 offset:39936
	global_load_lds_dwordx4 v[8:9], off
	v_lshl_add_u64 v[8:9], s[44:45], 0, v[144:145]
	s_mov_b32 m0, s28
	s_nop 0
	global_load_lds_dwordx4 v[8:9], off
	s_waitcnt vmcnt(8)
	s_waitcnt lgkmcnt(0)
	v_mfma_f32_16x16x32_bf16 v[130:133], v[134:137], v[188:191], v[130:133]
	v_mfma_f32_16x16x32_bf16 v[126:129], v[158:161], v[188:191], v[126:129]
	v_mfma_f32_16x16x32_bf16 v[122:125], v[134:137], v[196:199], v[122:125]
	v_mfma_f32_16x16x32_bf16 v[118:121], v[158:161], v[196:199], v[118:121]
	v_mfma_f32_16x16x32_bf16 v[114:117], v[134:137], v[204:207], v[114:117]
	v_mfma_f32_16x16x32_bf16 v[110:113], v[158:161], v[204:207], v[110:113]
	v_mfma_f32_16x16x32_bf16 v[106:109], v[134:137], v[212:215], v[106:109]
	v_mfma_f32_16x16x32_bf16 v[102:105], v[158:161], v[212:215], v[102:105]
	s_barrier
	s_setprio 1
	s_waitcnt lgkmcnt(0)
	v_mfma_f32_16x16x32_bf16 v[130:133], v[138:141], v[192:195], v[130:133]
	v_mfma_f32_16x16x32_bf16 v[126:129], v[168:171], v[192:195], v[126:129]
	v_mfma_f32_16x16x32_bf16 v[122:125], v[138:141], v[200:203], v[122:125]
	v_mfma_f32_16x16x32_bf16 v[118:121], v[168:171], v[200:203], v[118:121]
	v_mfma_f32_16x16x32_bf16 v[114:117], v[138:141], v[208:211], v[114:117]
	v_mfma_f32_16x16x32_bf16 v[110:113], v[168:171], v[208:211], v[110:113]
	v_mfma_f32_16x16x32_bf16 v[106:109], v[138:141], v[220:223], v[106:109]
	v_mfma_f32_16x16x32_bf16 v[102:105], v[168:171], v[220:223], v[102:105]
	s_setprio 0
	s_setprio 1
	v_mfma_f32_16x16x32_bf16 v[98:101], v[172:175], v[188:191], v[98:101]
	v_mfma_f32_16x16x32_bf16 v[94:97], v[180:183], v[188:191], v[94:97]
	v_mfma_f32_16x16x32_bf16 v[90:93], v[172:175], v[196:199], v[90:93]
	v_mfma_f32_16x16x32_bf16 v[86:89], v[180:183], v[196:199], v[86:89]
	v_mfma_f32_16x16x32_bf16 v[82:85], v[172:175], v[204:207], v[82:85]
	v_mfma_f32_16x16x32_bf16 v[78:81], v[180:183], v[204:207], v[78:81]
	v_mfma_f32_16x16x32_bf16 v[74:77], v[172:175], v[212:215], v[74:77]
	v_mfma_f32_16x16x32_bf16 v[70:73], v[180:183], v[212:215], v[70:73]
	v_mfma_f32_16x16x32_bf16 v[98:101], v[176:179], v[192:195], v[98:101]
	v_mfma_f32_16x16x32_bf16 v[94:97], v[184:187], v[192:195], v[94:97]
	v_mfma_f32_16x16x32_bf16 v[90:93], v[176:179], v[200:203], v[90:93]
	v_mfma_f32_16x16x32_bf16 v[86:89], v[184:187], v[200:203], v[86:89]
	v_mfma_f32_16x16x32_bf16 v[82:85], v[176:179], v[208:211], v[82:85]
	v_mfma_f32_16x16x32_bf16 v[78:81], v[184:187], v[208:211], v[78:81]
	v_mfma_f32_16x16x32_bf16 v[74:77], v[176:179], v[220:223], v[74:77]
	v_mfma_f32_16x16x32_bf16 v[70:73], v[184:187], v[220:223], v[70:73]
	s_setprio 0
	s_barrier
	s_add_i32 s44, s55, s24
	v_lshl_add_u64 v[8:9], v[162:163], 0, s[4:5]
	s_mov_b32 m0, s44
	ds_read_b128 v[188:191], v166 offset:49152
	ds_read_b128 v[192:195], v166 offset:50176
	ds_read_b128 v[196:199], v166 offset:51200
	ds_read_b128 v[200:203], v166 offset:52224
	ds_read_b128 v[204:207], v166 offset:53248
	ds_read_b128 v[208:211], v166 offset:54272
	ds_read_b128 v[212:215], v166 offset:55296
	ds_read_b128 v[220:223], v166 offset:56320
	global_load_lds_dwordx4 v[8:9], off
	s_add_i32 m0, s44, 0x2000
	s_add_u32 s20, s20, 0x40080
	v_lshl_add_u64 v[8:9], v[216:217], 0, s[4:5]
	s_addc_u32 s21, s21, 0
	s_add_i32 s44, s56, s24
	global_load_lds_dwordx4 v[8:9], off
	v_lshl_add_u64 v[8:9], s[20:21], 0, v[146:147]
	s_mov_b32 m0, s44
	s_nop 0
	global_load_lds_dwordx4 v[8:9], off
	v_lshl_add_u64 v[8:9], s[20:21], 0, v[142:143]
	s_add_i32 m0, s44, 0x2000
	s_nop 0
	global_load_lds_dwordx4 v[8:9], off
	v_lshl_add_u64 v[8:9], v[224:225], 0, s[4:5]
	s_mov_b32 m0, s31
	s_nop 0
	global_load_lds_dwordx4 v[8:9], off
	v_lshl_add_u64 v[8:9], v[226:227], 0, s[4:5]
	s_mov_b32 m0, s34
	s_nop 0
	global_load_lds_dwordx4 v[8:9], off
	s_waitcnt vmcnt(8)
	s_waitcnt lgkmcnt(0)
	v_mfma_f32_16x16x32_bf16 v[66:69], v[134:137], v[188:191], v[66:69]
	v_mfma_f32_16x16x32_bf16 v[62:65], v[158:161], v[188:191], v[62:65]
	v_mfma_f32_16x16x32_bf16 v[58:61], v[134:137], v[196:199], v[58:61]
	v_mfma_f32_16x16x32_bf16 v[54:57], v[158:161], v[196:199], v[54:57]
	v_mfma_f32_16x16x32_bf16 v[50:53], v[134:137], v[204:207], v[50:53]
	v_mfma_f32_16x16x32_bf16 v[46:49], v[158:161], v[204:207], v[46:49]
	v_mfma_f32_16x16x32_bf16 v[42:45], v[134:137], v[212:215], v[42:45]
	v_mfma_f32_16x16x32_bf16 v[38:41], v[158:161], v[212:215], v[38:41]
	s_barrier
	s_setprio 1
	s_waitcnt lgkmcnt(0)
	v_mfma_f32_16x16x32_bf16 v[66:69], v[138:141], v[192:195], v[66:69]
	v_mfma_f32_16x16x32_bf16 v[62:65], v[168:171], v[192:195], v[62:65]
	v_mfma_f32_16x16x32_bf16 v[58:61], v[138:141], v[200:203], v[58:61]
	v_mfma_f32_16x16x32_bf16 v[54:57], v[168:171], v[200:203], v[54:57]
	v_mfma_f32_16x16x32_bf16 v[50:53], v[138:141], v[208:211], v[50:53]
	v_mfma_f32_16x16x32_bf16 v[46:49], v[168:171], v[208:211], v[46:49]
	v_mfma_f32_16x16x32_bf16 v[42:45], v[138:141], v[220:223], v[42:45]
	v_mfma_f32_16x16x32_bf16 v[38:41], v[168:171], v[220:223], v[38:41]
	s_setprio 0
	s_setprio 1
	v_mfma_f32_16x16x32_bf16 v[34:37], v[172:175], v[188:191], v[34:37]
	v_mfma_f32_16x16x32_bf16 v[30:33], v[180:183], v[188:191], v[30:33]
	v_mfma_f32_16x16x32_bf16 v[26:29], v[172:175], v[196:199], v[26:29]
	v_mfma_f32_16x16x32_bf16 v[22:25], v[180:183], v[196:199], v[22:25]
	v_mfma_f32_16x16x32_bf16 v[18:21], v[172:175], v[204:207], v[18:21]
	v_mfma_f32_16x16x32_bf16 v[14:17], v[180:183], v[204:207], v[14:17]
	v_mfma_f32_16x16x32_bf16 v[8:11], v[172:175], v[212:215], v[10:13]
	v_mfma_f32_16x16x32_bf16 v[4:7], v[180:183], v[212:215], v[4:7]
	v_mfma_f32_16x16x32_bf16 v[34:37], v[176:179], v[192:195], v[34:37]
	v_mfma_f32_16x16x32_bf16 v[30:33], v[184:187], v[192:195], v[30:33]
	v_mfma_f32_16x16x32_bf16 v[26:29], v[176:179], v[200:203], v[26:29]
	v_mfma_f32_16x16x32_bf16 v[22:25], v[184:187], v[200:203], v[22:25]
	v_mfma_f32_16x16x32_bf16 v[18:21], v[176:179], v[208:211], v[18:21]
	v_mfma_f32_16x16x32_bf16 v[14:17], v[184:187], v[208:211], v[14:17]
	v_mfma_f32_16x16x32_bf16 v[10:13], v[176:179], v[220:223], v[8:11]
	v_mfma_f32_16x16x32_bf16 v[6:9], v[184:187], v[220:223], v[4:7]
	s_setprio 0
	s_barrier
	s_add_i32 s54, s54, 2
	s_add_u32 s18, s18, 0x100
	s_addc_u32 s19, s19, 0
	s_add_u32 s52, s52, 0x100
	s_addc_u32 s53, s53, 0
	s_cmp_gt_u32 s54, 13
	s_cbranch_scc0 .LBB0_772
	s_and_b64 vcc, exec, s[6:7]
	s_cbranch_vccz .LBB0_775
	s_barrier

.LBB0_866:
	ds_read_b128 v[34:37], v214
	ds_read_b128 v[46:49], v214 offset:1024
	ds_read_b128 v[54:57], v214 offset:2048
	ds_read_b128 v[62:65], v214 offset:3072
	ds_read_b128 v[150:153], v215
	ds_read_b128 v[154:157], v215 offset:1024
	ds_read_b128 v[158:161], v215 offset:2048
	ds_read_b128 v[162:165], v215 offset:3072
	s_add_u32 s38, s44, 0xfffc0080
	s_addc_u32 s39, s45, -1
	s_cmp_eq_u32 s58, 12
	s_cselect_b32 s55, s5, s39
	s_cselect_b32 s54, s19, s38
	s_cselect_b32 s53, s17, s57
	s_cselect_b32 s52, s37, s56
	v_lshl_add_u64 v[4:5], s[44:45], 0, v[194:195]
	s_add_i32 m0, s25, 0xc000
	ds_read_b128 v[166:169], v216
	ds_read_b128 v[170:173], v216 offset:1024
	ds_read_b128 v[174:177], v216 offset:2048
	ds_read_b128 v[178:181], v216 offset:3072
	ds_read_b128 v[182:185], v216 offset:4096
	ds_read_b128 v[202:205], v216 offset:5120
	ds_read_b128 v[206:209], v216 offset:6144
	ds_read_b128 v[220:223], v216 offset:7168
	global_load_lds_dwordx4 v[4:5], off
	v_lshl_add_u64 v[4:5], s[44:45], 0, v[196:197]
	s_add_i32 m0, s25, 0xe000
	s_nop 0
	global_load_lds_dwordx4 v[4:5], off
	s_waitcnt vmcnt(8)
	s_waitcnt lgkmcnt(0)
	v_mfma_f32_16x16x32_bf16 v[38:41], v[34:37], v[166:169], v[38:41]
	v_mfma_f32_16x16x32_bf16 v[146:149], v[54:57], v[166:169], v[146:149]
	v_mfma_f32_16x16x32_bf16 v[134:137], v[34:37], v[174:177], v[134:137]
	v_mfma_f32_16x16x32_bf16 v[130:133], v[54:57], v[174:177], v[130:133]
	v_mfma_f32_16x16x32_bf16 v[118:121], v[34:37], v[182:185], v[118:121]
	v_mfma_f32_16x16x32_bf16 v[114:117], v[54:57], v[182:185], v[114:117]
	v_mfma_f32_16x16x32_bf16 v[102:105], v[34:37], v[206:209], v[102:105]
	v_mfma_f32_16x16x32_bf16 v[98:101], v[54:57], v[206:209], v[98:101]
	s_barrier
	s_setprio 1
	s_waitcnt lgkmcnt(0)
	v_mfma_f32_16x16x32_bf16 v[38:41], v[46:49], v[170:173], v[38:41]
	v_mfma_f32_16x16x32_bf16 v[146:149], v[62:65], v[170:173], v[146:149]
	v_mfma_f32_16x16x32_bf16 v[134:137], v[46:49], v[178:181], v[134:137]
	v_mfma_f32_16x16x32_bf16 v[130:133], v[62:65], v[178:181], v[130:133]
	v_mfma_f32_16x16x32_bf16 v[118:121], v[46:49], v[202:205], v[118:121]
	v_mfma_f32_16x16x32_bf16 v[114:117], v[62:65], v[202:205], v[114:117]
	v_mfma_f32_16x16x32_bf16 v[102:105], v[46:49], v[220:223], v[102:105]
	v_mfma_f32_16x16x32_bf16 v[98:101], v[62:65], v[220:223], v[98:101]
	s_setprio 0
	s_setprio 1
	v_mfma_f32_16x16x32_bf16 v[142:145], v[150:153], v[166:169], v[142:145]
	v_mfma_f32_16x16x32_bf16 v[138:141], v[158:161], v[166:169], v[138:141]
	v_mfma_f32_16x16x32_bf16 v[126:129], v[150:153], v[174:177], v[126:129]
	v_mfma_f32_16x16x32_bf16 v[122:125], v[158:161], v[174:177], v[122:125]
	v_mfma_f32_16x16x32_bf16 v[110:113], v[150:153], v[182:185], v[110:113]
	v_mfma_f32_16x16x32_bf16 v[106:109], v[158:161], v[182:185], v[106:109]
	v_mfma_f32_16x16x32_bf16 v[94:97], v[150:153], v[206:209], v[94:97]
	v_mfma_f32_16x16x32_bf16 v[90:93], v[158:161], v[206:209], v[90:93]
	v_mfma_f32_16x16x32_bf16 v[142:145], v[154:157], v[170:173], v[142:145]
	v_mfma_f32_16x16x32_bf16 v[138:141], v[162:165], v[170:173], v[138:141]
	v_mfma_f32_16x16x32_bf16 v[126:129], v[154:157], v[178:181], v[126:129]
	v_mfma_f32_16x16x32_bf16 v[122:125], v[162:165], v[178:181], v[122:125]
	v_mfma_f32_16x16x32_bf16 v[110:113], v[154:157], v[202:205], v[110:113]
	v_mfma_f32_16x16x32_bf16 v[106:109], v[162:165], v[202:205], v[106:109]
	v_mfma_f32_16x16x32_bf16 v[94:97], v[154:157], v[220:223], v[94:97]
	v_mfma_f32_16x16x32_bf16 v[90:93], v[162:165], v[220:223], v[90:93]
	s_setprio 0
	s_barrier
	s_add_i32 s38, s34, s24
	v_lshl_add_u64 v[210:211], s[52:53], 0, v[186:187]
	s_mov_b32 m0, s38
	ds_read_b128 v[166:169], v216 offset:16384
	ds_read_b128 v[170:173], v216 offset:17408
	ds_read_b128 v[174:177], v216 offset:18432
	ds_read_b128 v[178:181], v216 offset:19456
	ds_read_b128 v[182:185], v216 offset:20480
	ds_read_b128 v[202:205], v216 offset:21504
	ds_read_b128 v[206:209], v216 offset:22528
	ds_read_b128 v[220:223], v216 offset:23552
	global_load_lds_dwordx4 v[210:211], off
	s_add_i32 m0, s38, 0x2000
	s_add_u32 s38, s52, 0x40000
	v_lshl_add_u64 v[224:225], s[52:53], 0, v[188:189]
	s_addc_u32 s39, s53, 0
	s_add_i32 s59, s35, s24
	global_load_lds_dwordx4 v[224:225], off
	v_lshl_add_u64 v[4:5], s[38:39], 0, v[186:187]
	s_mov_b32 m0, s59
	v_lshl_add_u64 v[226:227], s[54:55], 0, v[186:187]
	global_load_lds_dwordx4 v[4:5], off
	v_lshl_add_u64 v[4:5], s[38:39], 0, v[188:189]
	s_add_i32 m0, s59, 0x2000
	v_lshl_add_u64 v[228:229], s[54:55], 0, v[188:189]
	global_load_lds_dwordx4 v[4:5], off
	s_mov_b32 m0, s25
	s_nop 0
	global_load_lds_dwordx4 v[226:227], off
	s_mov_b32 m0, s26
	s_nop 0
	global_load_lds_dwordx4 v[228:229], off
	s_waitcnt vmcnt(8)
	s_waitcnt lgkmcnt(0)
	v_mfma_f32_16x16x32_bf16 v[86:89], v[34:37], v[166:169], v[86:89]
	v_mfma_f32_16x16x32_bf16 v[82:85], v[54:57], v[166:169], v[82:85]
	v_mfma_f32_16x16x32_bf16 v[70:73], v[34:37], v[174:177], v[70:73]
	v_mfma_f32_16x16x32_bf16 v[66:69], v[54:57], v[174:177], v[66:69]
	v_mfma_f32_16x16x32_bf16 v[42:45], v[34:37], v[182:185], v[42:45]
	v_mfma_f32_16x16x32_bf16 v[30:33], v[54:57], v[182:185], v[30:33]
	v_mfma_f32_16x16x32_bf16 v[18:21], v[34:37], v[206:209], v[18:21]
	v_mfma_f32_16x16x32_bf16 v[14:17], v[54:57], v[206:209], v[14:17]
	s_barrier
	s_setprio 1
	s_waitcnt lgkmcnt(0)
	v_mfma_f32_16x16x32_bf16 v[86:89], v[46:49], v[170:173], v[86:89]
	v_mfma_f32_16x16x32_bf16 v[82:85], v[62:65], v[170:173], v[82:85]
	v_mfma_f32_16x16x32_bf16 v[70:73], v[46:49], v[178:181], v[70:73]
	v_mfma_f32_16x16x32_bf16 v[66:69], v[62:65], v[178:181], v[66:69]
	v_mfma_f32_16x16x32_bf16 v[42:45], v[46:49], v[202:205], v[42:45]
	v_mfma_f32_16x16x32_bf16 v[30:33], v[62:65], v[202:205], v[30:33]
	v_mfma_f32_16x16x32_bf16 v[18:21], v[46:49], v[220:223], v[18:21]
	v_mfma_f32_16x16x32_bf16 v[14:17], v[62:65], v[220:223], v[14:17]
	s_setprio 0
	s_setprio 1
	v_mfma_f32_16x16x32_bf16 v[50:53], v[158:161], v[174:177], v[50:53]
	v_mfma_f32_16x16x32_bf16 v[26:29], v[150:153], v[182:185], v[26:29]
	v_mfma_f32_16x16x32_bf16 v[22:25], v[158:161], v[182:185], v[22:25]
	v_mfma_f32_16x16x32_bf16 v[10:13], v[150:153], v[206:209], v[10:13]
	v_mfma_f32_16x16x32_bf16 v[4:7], v[158:161], v[206:209], v[6:9]
	v_mfma_f32_16x16x32_bf16 v[34:37], v[150:153], v[166:169], v[78:81]
	v_mfma_f32_16x16x32_bf16 v[46:49], v[158:161], v[166:169], v[74:77]
	v_mfma_f32_16x16x32_bf16 v[54:57], v[150:153], v[174:177], v[58:61]
	v_mfma_f32_16x16x32_bf16 v[50:53], v[162:165], v[178:181], v[50:53]
	v_mfma_f32_16x16x32_bf16 v[26:29], v[154:157], v[202:205], v[26:29]
	v_mfma_f32_16x16x32_bf16 v[22:25], v[162:165], v[202:205], v[22:25]
	v_mfma_f32_16x16x32_bf16 v[10:13], v[154:157], v[220:223], v[10:13]
	v_mfma_f32_16x16x32_bf16 v[4:7], v[162:165], v[220:223], v[4:7]
	v_mfma_f32_16x16x32_bf16 v[34:37], v[154:157], v[170:173], v[34:37]
	v_mfma_f32_16x16x32_bf16 v[46:49], v[162:165], v[170:173], v[46:49]
	v_mfma_f32_16x16x32_bf16 v[54:57], v[154:157], v[178:181], v[54:57]
	s_setprio 0
	s_barrier
	s_add_i32 s59, 0, 0x18000
	v_add_u32_e32 v3, s59, v212
	s_add_i32 s60, 0, 0x1c000
	ds_read_b128 v[58:61], v3
	ds_read_b128 v[62:65], v3 offset:1024
	ds_read_b128 v[74:77], v3 offset:2048
	ds_read_b128 v[78:81], v3 offset:3072
	v_add_u32_e32 v3, s60, v212
	ds_read_b128 v[150:153], v3
	ds_read_b128 v[154:157], v3 offset:1024
	ds_read_b128 v[158:161], v3 offset:2048
	ds_read_b128 v[162:165], v3 offset:3072
	s_add_u32 s38, s54, 0x40000
	s_addc_u32 s39, s55, 0
	s_mov_b32 m0, s27
	v_lshl_add_u64 v[8:9], s[38:39], 0, v[186:187]
	ds_read_b128 v[166:169], v216 offset:32768
	ds_read_b128 v[170:173], v216 offset:33792
	ds_read_b128 v[174:177], v216 offset:34816
	ds_read_b128 v[178:181], v216 offset:35840
	ds_read_b128 v[182:185], v216 offset:36864
	ds_read_b128 v[202:205], v216 offset:37888
	ds_read_b128 v[206:209], v216 offset:38912
	ds_read_b128 v[220:223], v216 offset:39936
	global_load_lds_dwordx4 v[8:9], off
	v_lshl_add_u64 v[8:9], s[38:39], 0, v[188:189]
	s_mov_b32 m0, s28
	s_nop 0
	global_load_lds_dwordx4 v[8:9], off
	s_waitcnt vmcnt(8)
	s_waitcnt lgkmcnt(0)
	v_mfma_f32_16x16x32_bf16 v[38:41], v[58:61], v[166:169], v[38:41]
	v_mfma_f32_16x16x32_bf16 v[146:149], v[74:77], v[166:169], v[146:149]
	v_mfma_f32_16x16x32_bf16 v[134:137], v[58:61], v[174:177], v[134:137]
	v_mfma_f32_16x16x32_bf16 v[130:133], v[74:77], v[174:177], v[130:133]
	v_mfma_f32_16x16x32_bf16 v[118:121], v[58:61], v[182:185], v[118:121]
	v_mfma_f32_16x16x32_bf16 v[114:117], v[74:77], v[182:185], v[114:117]
	v_mfma_f32_16x16x32_bf16 v[102:105], v[58:61], v[206:209], v[102:105]
	v_mfma_f32_16x16x32_bf16 v[98:101], v[74:77], v[206:209], v[98:101]
	s_barrier
	s_setprio 1
	s_waitcnt lgkmcnt(0)
	v_mfma_f32_16x16x32_bf16 v[38:41], v[62:65], v[170:173], v[38:41]
	v_mfma_f32_16x16x32_bf16 v[146:149], v[78:81], v[170:173], v[146:149]
	v_mfma_f32_16x16x32_bf16 v[134:137], v[62:65], v[178:181], v[134:137]
	v_mfma_f32_16x16x32_bf16 v[130:133], v[78:81], v[178:181], v[130:133]
	v_mfma_f32_16x16x32_bf16 v[118:121], v[62:65], v[202:205], v[118:121]
	v_mfma_f32_16x16x32_bf16 v[114:117], v[78:81], v[202:205], v[114:117]
	v_mfma_f32_16x16x32_bf16 v[102:105], v[62:65], v[220:223], v[102:105]
	v_mfma_f32_16x16x32_bf16 v[98:101], v[78:81], v[220:223], v[98:101]
	s_setprio 0
	s_setprio 1
	v_mfma_f32_16x16x32_bf16 v[142:145], v[150:153], v[166:169], v[142:145]
	v_mfma_f32_16x16x32_bf16 v[138:141], v[158:161], v[166:169], v[138:141]
	v_mfma_f32_16x16x32_bf16 v[126:129], v[150:153], v[174:177], v[126:129]
	v_mfma_f32_16x16x32_bf16 v[122:125], v[158:161], v[174:177], v[122:125]
	v_mfma_f32_16x16x32_bf16 v[110:113], v[150:153], v[182:185], v[110:113]
	v_mfma_f32_16x16x32_bf16 v[106:109], v[158:161], v[182:185], v[106:109]
	v_mfma_f32_16x16x32_bf16 v[94:97], v[150:153], v[206:209], v[94:97]
	v_mfma_f32_16x16x32_bf16 v[90:93], v[158:161], v[206:209], v[90:93]
	v_mfma_f32_16x16x32_bf16 v[142:145], v[154:157], v[170:173], v[142:145]
	v_mfma_f32_16x16x32_bf16 v[138:141], v[162:165], v[170:173], v[138:141]
	v_mfma_f32_16x16x32_bf16 v[126:129], v[154:157], v[178:181], v[126:129]
	v_mfma_f32_16x16x32_bf16 v[122:125], v[162:165], v[178:181], v[122:125]
	v_mfma_f32_16x16x32_bf16 v[110:113], v[154:157], v[202:205], v[110:113]
	v_mfma_f32_16x16x32_bf16 v[106:109], v[162:165], v[202:205], v[106:109]
	v_mfma_f32_16x16x32_bf16 v[94:97], v[154:157], v[220:223], v[94:97]
	v_mfma_f32_16x16x32_bf16 v[90:93], v[162:165], v[220:223], v[90:93]
	s_setprio 0
	s_barrier
	s_add_i32 s38, s59, s24
	v_lshl_add_u64 v[8:9], v[210:211], 0, s[12:13]
	s_mov_b32 m0, s38
	ds_read_b128 v[166:169], v216 offset:49152
	ds_read_b128 v[170:173], v216 offset:50176
	ds_read_b128 v[174:177], v216 offset:51200
	ds_read_b128 v[178:181], v216 offset:52224
	ds_read_b128 v[182:185], v216 offset:53248
	ds_read_b128 v[202:205], v216 offset:54272
	ds_read_b128 v[206:209], v216 offset:55296
	ds_read_b128 v[220:223], v216 offset:56320
	global_load_lds_dwordx4 v[8:9], off
	s_add_i32 m0, s38, 0x2000
	s_add_u32 s38, s52, 0x40080
	v_lshl_add_u64 v[8:9], v[224:225], 0, s[12:13]
	s_addc_u32 s39, s53, 0
	s_add_i32 s52, s60, s24
	global_load_lds_dwordx4 v[8:9], off
	v_lshl_add_u64 v[8:9], s[38:39], 0, v[186:187]
	s_mov_b32 m0, s52
	s_nop 0
	global_load_lds_dwordx4 v[8:9], off
	v_lshl_add_u64 v[8:9], s[38:39], 0, v[188:189]
	s_add_i32 m0, s52, 0x2000
	s_nop 0
	global_load_lds_dwordx4 v[8:9], off
	v_lshl_add_u64 v[8:9], v[226:227], 0, s[12:13]
	s_mov_b32 m0, s30
	s_nop 0
	global_load_lds_dwordx4 v[8:9], off
	v_lshl_add_u64 v[8:9], v[228:229], 0, s[12:13]
	s_mov_b32 m0, s31
	s_nop 0
	global_load_lds_dwordx4 v[8:9], off
	s_waitcnt vmcnt(8)
	s_waitcnt lgkmcnt(0)
	v_mfma_f32_16x16x32_bf16 v[86:89], v[58:61], v[166:169], v[86:89]
	v_mfma_f32_16x16x32_bf16 v[82:85], v[74:77], v[166:169], v[82:85]
	v_mfma_f32_16x16x32_bf16 v[70:73], v[58:61], v[174:177], v[70:73]
	v_mfma_f32_16x16x32_bf16 v[66:69], v[74:77], v[174:177], v[66:69]
	v_mfma_f32_16x16x32_bf16 v[42:45], v[58:61], v[182:185], v[42:45]
	v_mfma_f32_16x16x32_bf16 v[30:33], v[74:77], v[182:185], v[30:33]
	v_mfma_f32_16x16x32_bf16 v[18:21], v[58:61], v[206:209], v[18:21]
	v_mfma_f32_16x16x32_bf16 v[14:17], v[74:77], v[206:209], v[14:17]
	s_barrier
	s_setprio 1
	s_waitcnt lgkmcnt(0)
	v_mfma_f32_16x16x32_bf16 v[86:89], v[62:65], v[170:173], v[86:89]
	v_mfma_f32_16x16x32_bf16 v[82:85], v[78:81], v[170:173], v[82:85]
	v_mfma_f32_16x16x32_bf16 v[70:73], v[62:65], v[178:181], v[70:73]
	v_mfma_f32_16x16x32_bf16 v[66:69], v[78:81], v[178:181], v[66:69]
	v_mfma_f32_16x16x32_bf16 v[42:45], v[62:65], v[202:205], v[42:45]
	v_mfma_f32_16x16x32_bf16 v[30:33], v[78:81], v[202:205], v[30:33]
	v_mfma_f32_16x16x32_bf16 v[18:21], v[62:65], v[220:223], v[18:21]
	v_mfma_f32_16x16x32_bf16 v[14:17], v[78:81], v[220:223], v[14:17]
	s_setprio 0
	s_setprio 1
	v_mfma_f32_16x16x32_bf16 v[34:37], v[150:153], v[166:169], v[34:37]
	v_mfma_f32_16x16x32_bf16 v[78:81], v[154:157], v[170:173], v[34:37]
	v_mfma_f32_16x16x32_bf16 v[34:37], v[158:161], v[166:169], v[46:49]
	v_mfma_f32_16x16x32_bf16 v[74:77], v[162:165], v[170:173], v[34:37]
	v_mfma_f32_16x16x32_bf16 v[34:37], v[150:153], v[174:177], v[54:57]
	v_mfma_f32_16x16x32_bf16 v[58:61], v[154:157], v[178:181], v[34:37]
	v_mfma_f32_16x16x32_bf16 v[34:37], v[158:161], v[174:177], v[50:53]
	v_mfma_f32_16x16x32_bf16 v[26:29], v[150:153], v[182:185], v[26:29]
	v_mfma_f32_16x16x32_bf16 v[22:25], v[158:161], v[182:185], v[22:25]
	v_mfma_f32_16x16x32_bf16 v[8:11], v[150:153], v[206:209], v[10:13]
	v_mfma_f32_16x16x32_bf16 v[4:7], v[158:161], v[206:209], v[4:7]
	v_mfma_f32_16x16x32_bf16 v[50:53], v[162:165], v[178:181], v[34:37]
	v_mfma_f32_16x16x32_bf16 v[26:29], v[154:157], v[202:205], v[26:29]
	v_mfma_f32_16x16x32_bf16 v[22:25], v[162:165], v[202:205], v[22:25]
	v_mfma_f32_16x16x32_bf16 v[10:13], v[154:157], v[220:223], v[8:11]
	v_mfma_f32_16x16x32_bf16 v[6:9], v[162:165], v[220:223], v[4:7]
	s_setprio 0
	s_barrier
	s_add_i32 s58, s58, 2
	s_add_u32 s44, s44, 0x100
	s_addc_u32 s45, s45, 0
	s_add_u32 s56, s56, 0x100
	s_addc_u32 s57, s57, 0
	s_cmp_gt_u32 s58, 13
	s_cbranch_scc0 .LBB0_866
	s_and_b64 vcc, exec, s[14:15]
	s_cbranch_vccz .LBB0_869
	s_barrier

.LBB0_1180:
	ds_read_b128 v[54:57], v238
	ds_read_b128 v[134:137], v238 offset:1024
	ds_read_b128 v[158:161], v238 offset:2048
	ds_read_b128 v[162:165], v238 offset:3072
	ds_read_b128 v[166:169], v239
	ds_read_b128 v[170:173], v239 offset:1024
	ds_read_b128 v[174:177], v239 offset:2048
	ds_read_b128 v[178:181], v239 offset:3072
	s_add_u32 s0, s60, 0x100
	s_addc_u32 s1, s61, 0
	s_cmp_eq_u32 s38, 12
	s_cselect_b32 s65, s19, s1
	s_cselect_b32 s64, s18, s0
	s_cselect_b32 s63, s17, vcc_hi
	s_cselect_b32 s62, s93, vcc_lo
	v_lshl_add_u64 v[214:215], s[60:61], 0, v[150:151]
	s_add_i32 m0, s73, 0xc000
	ds_read_b128 v[182:185], v240
	ds_read_b128 v[186:189], v240 offset:1024
	ds_read_b128 v[190:193], v240 offset:2048
	ds_read_b128 v[194:197], v240 offset:3072
	ds_read_b128 v[198:201], v240 offset:4096
	ds_read_b128 v[202:205], v240 offset:5120
	ds_read_b128 v[206:209], v240 offset:6144
	ds_read_b128 v[210:213], v240 offset:7168
	global_load_lds_dwordx4 v[214:215], off
	v_lshl_add_u64 v[214:215], s[60:61], 0, v[152:153]
	s_add_i32 m0, s73, 0xe000
	s_nop 0
	global_load_lds_dwordx4 v[214:215], off
	s_waitcnt vmcnt(8)
	s_waitcnt lgkmcnt(0)
	v_mfma_f32_16x16x32_bf16 v[126:129], v[54:57], v[182:185], v[126:129]
	v_mfma_f32_16x16x32_bf16 v[122:125], v[158:161], v[182:185], v[122:125]
	v_mfma_f32_16x16x32_bf16 v[118:121], v[54:57], v[190:193], v[118:121]
	v_mfma_f32_16x16x32_bf16 v[114:117], v[158:161], v[190:193], v[114:117]
	v_mfma_f32_16x16x32_bf16 v[50:53], v[54:57], v[198:201], v[50:53]
	v_mfma_f32_16x16x32_bf16 v[22:25], v[158:161], v[198:201], v[22:25]
	v_mfma_f32_16x16x32_bf16 v[62:65], v[54:57], v[206:209], v[62:65]
	v_mfma_f32_16x16x32_bf16 v[130:133], v[158:161], v[206:209], v[130:133]
	s_barrier
	s_setprio 1
	s_waitcnt lgkmcnt(0)
	v_mfma_f32_16x16x32_bf16 v[126:129], v[134:137], v[186:189], v[126:129]
	v_mfma_f32_16x16x32_bf16 v[122:125], v[162:165], v[186:189], v[122:125]
	v_mfma_f32_16x16x32_bf16 v[118:121], v[134:137], v[194:197], v[118:121]
	v_mfma_f32_16x16x32_bf16 v[114:117], v[162:165], v[194:197], v[114:117]
	v_mfma_f32_16x16x32_bf16 v[50:53], v[134:137], v[202:205], v[50:53]
	v_mfma_f32_16x16x32_bf16 v[22:25], v[162:165], v[202:205], v[22:25]
	v_mfma_f32_16x16x32_bf16 v[62:65], v[134:137], v[210:213], v[62:65]
	v_mfma_f32_16x16x32_bf16 v[130:133], v[162:165], v[210:213], v[130:133]
	s_setprio 0
	s_setprio 1
	v_mfma_f32_16x16x32_bf16 v[110:113], v[166:169], v[182:185], v[110:113]
	v_mfma_f32_16x16x32_bf16 v[106:109], v[174:177], v[182:185], v[106:109]
	v_mfma_f32_16x16x32_bf16 v[102:105], v[166:169], v[190:193], v[102:105]
	v_mfma_f32_16x16x32_bf16 v[98:101], v[174:177], v[190:193], v[98:101]
	v_mfma_f32_16x16x32_bf16 v[30:33], v[166:169], v[198:201], v[30:33]
	v_mfma_f32_16x16x32_bf16 v[18:21], v[174:177], v[198:201], v[18:21]
	v_mfma_f32_16x16x32_bf16 v[58:61], v[166:169], v[206:209], v[58:61]
	v_mfma_f32_16x16x32_bf16 v[26:29], v[174:177], v[206:209], v[26:29]
	v_mfma_f32_16x16x32_bf16 v[110:113], v[170:173], v[186:189], v[110:113]
	v_mfma_f32_16x16x32_bf16 v[106:109], v[178:181], v[186:189], v[106:109]
	v_mfma_f32_16x16x32_bf16 v[102:105], v[170:173], v[194:197], v[102:105]
	v_mfma_f32_16x16x32_bf16 v[98:101], v[178:181], v[194:197], v[98:101]
	v_mfma_f32_16x16x32_bf16 v[30:33], v[170:173], v[202:205], v[30:33]
	v_mfma_f32_16x16x32_bf16 v[18:21], v[178:181], v[202:205], v[18:21]
	v_mfma_f32_16x16x32_bf16 v[58:61], v[170:173], v[210:213], v[58:61]
	v_mfma_f32_16x16x32_bf16 v[26:29], v[178:181], v[210:213], v[26:29]
	s_setprio 0
	s_barrier
	s_add_i32 s39, s30, s89
	v_lshl_add_u64 v[214:215], s[62:63], 0, v[140:141]
	s_mov_b32 m0, s39
	ds_read_b128 v[182:185], v240 offset:16384
	ds_read_b128 v[186:189], v240 offset:17408
	ds_read_b128 v[190:193], v240 offset:18432
	ds_read_b128 v[194:197], v240 offset:19456
	ds_read_b128 v[198:201], v240 offset:20480
	ds_read_b128 v[202:205], v240 offset:21504
	ds_read_b128 v[206:209], v240 offset:22528
	ds_read_b128 v[210:213], v240 offset:23552
	global_load_lds_dwordx4 v[214:215], off
	s_add_i32 m0, s39, 0x2000
	s_add_u32 s60, s62, 0x40000
	v_lshl_add_u64 v[216:217], s[62:63], 0, v[144:145]
	s_addc_u32 s61, s63, 0
	s_add_i32 s39, s31, s89
	global_load_lds_dwordx4 v[216:217], off
	v_lshl_add_u64 v[244:245], s[60:61], 0, v[140:141]
	s_mov_b32 m0, s39
	v_lshl_add_u64 v[246:247], s[64:65], 0, v[142:143]
	global_load_lds_dwordx4 v[244:245], off
	v_lshl_add_u64 v[244:245], s[60:61], 0, v[144:145]
	s_add_i32 m0, s39, 0x2000
	s_nop 0
	global_load_lds_dwordx4 v[244:245], off
	v_lshl_add_u64 v[244:245], s[64:65], 0, v[138:139]
	s_mov_b32 m0, s73
	s_nop 0
	global_load_lds_dwordx4 v[244:245], off
	s_mov_b32 m0, s24
	s_nop 0
	global_load_lds_dwordx4 v[246:247], off
	s_waitcnt vmcnt(8)
	s_waitcnt lgkmcnt(0)
	v_mfma_f32_16x16x32_bf16 v[94:97], v[54:57], v[182:185], v[94:97]
	v_mfma_f32_16x16x32_bf16 v[90:93], v[158:161], v[182:185], v[90:93]
	v_mfma_f32_16x16x32_bf16 v[86:89], v[54:57], v[190:193], v[86:89]
	v_mfma_f32_16x16x32_bf16 v[82:85], v[158:161], v[190:193], v[82:85]
	v_mfma_f32_16x16x32_bf16 v[34:37], v[54:57], v[198:201], v[34:37]
	v_mfma_f32_16x16x32_bf16 v[6:9], v[158:161], v[198:201], v[6:9]
	v_mfma_f32_16x16x32_bf16 v[42:45], v[54:57], v[206:209], v[42:45]
	v_mfma_f32_16x16x32_bf16 v[10:13], v[158:161], v[206:209], v[10:13]
	s_barrier
	s_setprio 1
	s_waitcnt lgkmcnt(0)
	v_mfma_f32_16x16x32_bf16 v[94:97], v[134:137], v[186:189], v[94:97]
	v_mfma_f32_16x16x32_bf16 v[90:93], v[162:165], v[186:189], v[90:93]
	v_mfma_f32_16x16x32_bf16 v[86:89], v[134:137], v[194:197], v[86:89]
	v_mfma_f32_16x16x32_bf16 v[82:85], v[162:165], v[194:197], v[82:85]
	v_mfma_f32_16x16x32_bf16 v[34:37], v[134:137], v[202:205], v[34:37]
	v_mfma_f32_16x16x32_bf16 v[6:9], v[162:165], v[202:205], v[6:9]
	v_mfma_f32_16x16x32_bf16 v[42:45], v[134:137], v[210:213], v[42:45]
	v_mfma_f32_16x16x32_bf16 v[10:13], v[162:165], v[210:213], v[10:13]
	s_setprio 0
	s_setprio 1
	v_mfma_f32_16x16x32_bf16 v[74:77], v[174:177], v[182:185], v[74:77]
	v_mfma_f32_16x16x32_bf16 v[70:73], v[166:169], v[190:193], v[70:73]
	v_mfma_f32_16x16x32_bf16 v[66:69], v[174:177], v[190:193], v[66:69]
	v_mfma_f32_16x16x32_bf16 v[38:41], v[166:169], v[198:201], v[38:41]
	v_mfma_f32_16x16x32_bf16 v[2:5], v[174:177], v[198:201], v[2:5]
	v_mfma_f32_16x16x32_bf16 v[46:49], v[166:169], v[206:209], v[46:49]
	v_mfma_f32_16x16x32_bf16 v[14:17], v[174:177], v[206:209], v[14:17]
	v_mfma_f32_16x16x32_bf16 v[54:57], v[166:169], v[182:185], v[78:81]
	v_mfma_f32_16x16x32_bf16 v[74:77], v[178:181], v[186:189], v[74:77]
	v_mfma_f32_16x16x32_bf16 v[70:73], v[170:173], v[194:197], v[70:73]
	v_mfma_f32_16x16x32_bf16 v[66:69], v[178:181], v[194:197], v[66:69]
	v_mfma_f32_16x16x32_bf16 v[38:41], v[170:173], v[202:205], v[38:41]
	v_mfma_f32_16x16x32_bf16 v[2:5], v[178:181], v[202:205], v[2:5]
	v_mfma_f32_16x16x32_bf16 v[46:49], v[170:173], v[210:213], v[46:49]
	v_mfma_f32_16x16x32_bf16 v[14:17], v[178:181], v[210:213], v[14:17]
	v_mfma_f32_16x16x32_bf16 v[54:57], v[170:173], v[186:189], v[54:57]
	s_setprio 0
	s_barrier
	s_add_i32 s39, 0, 0x18000
	v_add_u32_e32 v146, s39, v1
	s_add_i32 s94, 0, 0x1c000
	ds_read_b128 v[78:81], v146
	ds_read_b128 v[134:137], v146 offset:1024
	ds_read_b128 v[158:161], v146 offset:2048
	ds_read_b128 v[162:165], v146 offset:3072
	v_add_u32_e32 v146, s94, v1
	ds_read_b128 v[166:169], v146
	ds_read_b128 v[170:173], v146 offset:1024
	ds_read_b128 v[174:177], v146 offset:2048
	ds_read_b128 v[178:181], v146 offset:3072
	s_add_u32 s60, s64, 0x40000
	s_addc_u32 s61, s65, 0
	s_mov_b32 m0, s25
	v_lshl_add_u64 v[248:249], s[60:61], 0, v[138:139]
	ds_read_b128 v[182:185], v240 offset:32768
	ds_read_b128 v[186:189], v240 offset:33792
	ds_read_b128 v[190:193], v240 offset:34816
	ds_read_b128 v[194:197], v240 offset:35840
	ds_read_b128 v[198:201], v240 offset:36864
	ds_read_b128 v[202:205], v240 offset:37888
	ds_read_b128 v[206:209], v240 offset:38912
	ds_read_b128 v[210:213], v240 offset:39936
	global_load_lds_dwordx4 v[248:249], off
	v_lshl_add_u64 v[248:249], s[60:61], 0, v[142:143]
	s_mov_b32 m0, s26
	s_nop 0
	global_load_lds_dwordx4 v[248:249], off
	s_waitcnt vmcnt(8)
	s_waitcnt lgkmcnt(0)
	v_mfma_f32_16x16x32_bf16 v[126:129], v[78:81], v[182:185], v[126:129]
	v_mfma_f32_16x16x32_bf16 v[122:125], v[158:161], v[182:185], v[122:125]
	v_mfma_f32_16x16x32_bf16 v[118:121], v[78:81], v[190:193], v[118:121]
	v_mfma_f32_16x16x32_bf16 v[114:117], v[158:161], v[190:193], v[114:117]
	v_mfma_f32_16x16x32_bf16 v[50:53], v[78:81], v[198:201], v[50:53]
	v_mfma_f32_16x16x32_bf16 v[22:25], v[158:161], v[198:201], v[22:25]
	v_mfma_f32_16x16x32_bf16 v[62:65], v[78:81], v[206:209], v[62:65]
	v_mfma_f32_16x16x32_bf16 v[130:133], v[158:161], v[206:209], v[130:133]
	s_barrier
	s_setprio 1
	s_waitcnt lgkmcnt(0)
	v_mfma_f32_16x16x32_bf16 v[126:129], v[134:137], v[186:189], v[126:129]
	v_mfma_f32_16x16x32_bf16 v[122:125], v[162:165], v[186:189], v[122:125]
	v_mfma_f32_16x16x32_bf16 v[118:121], v[134:137], v[194:197], v[118:121]
	v_mfma_f32_16x16x32_bf16 v[114:117], v[162:165], v[194:197], v[114:117]
	v_mfma_f32_16x16x32_bf16 v[50:53], v[134:137], v[202:205], v[50:53]
	v_mfma_f32_16x16x32_bf16 v[22:25], v[162:165], v[202:205], v[22:25]
	v_mfma_f32_16x16x32_bf16 v[62:65], v[134:137], v[210:213], v[62:65]
	v_mfma_f32_16x16x32_bf16 v[130:133], v[162:165], v[210:213], v[130:133]
	s_setprio 0
	s_setprio 1
	v_mfma_f32_16x16x32_bf16 v[110:113], v[166:169], v[182:185], v[110:113]
	v_mfma_f32_16x16x32_bf16 v[106:109], v[174:177], v[182:185], v[106:109]
	v_mfma_f32_16x16x32_bf16 v[102:105], v[166:169], v[190:193], v[102:105]
	v_mfma_f32_16x16x32_bf16 v[98:101], v[174:177], v[190:193], v[98:101]
	v_mfma_f32_16x16x32_bf16 v[30:33], v[166:169], v[198:201], v[30:33]
	v_mfma_f32_16x16x32_bf16 v[18:21], v[174:177], v[198:201], v[18:21]
	v_mfma_f32_16x16x32_bf16 v[58:61], v[166:169], v[206:209], v[58:61]
	v_mfma_f32_16x16x32_bf16 v[26:29], v[174:177], v[206:209], v[26:29]
	v_mfma_f32_16x16x32_bf16 v[110:113], v[170:173], v[186:189], v[110:113]
	v_mfma_f32_16x16x32_bf16 v[106:109], v[178:181], v[186:189], v[106:109]
	v_mfma_f32_16x16x32_bf16 v[102:105], v[170:173], v[194:197], v[102:105]
	v_mfma_f32_16x16x32_bf16 v[98:101], v[178:181], v[194:197], v[98:101]
	v_mfma_f32_16x16x32_bf16 v[30:33], v[170:173], v[202:205], v[30:33]
	v_mfma_f32_16x16x32_bf16 v[18:21], v[178:181], v[202:205], v[18:21]
	v_mfma_f32_16x16x32_bf16 v[58:61], v[170:173], v[210:213], v[58:61]
	v_mfma_f32_16x16x32_bf16 v[26:29], v[178:181], v[210:213], v[26:29]
	s_setprio 0
	s_barrier
	s_add_i32 s39, s39, s89
	v_lshl_add_u64 v[214:215], v[214:215], 0, s[76:77]
	s_mov_b32 m0, s39
	ds_read_b128 v[182:185], v240 offset:49152
	ds_read_b128 v[186:189], v240 offset:50176
	ds_read_b128 v[190:193], v240 offset:51200
	ds_read_b128 v[194:197], v240 offset:52224
	ds_read_b128 v[198:201], v240 offset:53248
	ds_read_b128 v[202:205], v240 offset:54272
	ds_read_b128 v[206:209], v240 offset:55296
	ds_read_b128 v[210:213], v240 offset:56320
	global_load_lds_dwordx4 v[214:215], off
	s_add_i32 m0, s39, 0x2000
	s_add_u32 s60, s62, 0x40080
	v_lshl_add_u64 v[214:215], v[216:217], 0, s[76:77]
	s_addc_u32 s61, s63, 0
	s_add_i32 s39, s94, s89
	global_load_lds_dwordx4 v[214:215], off
	v_lshl_add_u64 v[214:215], s[60:61], 0, v[140:141]
	s_mov_b32 m0, s39
	s_nop 0
	global_load_lds_dwordx4 v[214:215], off
	v_lshl_add_u64 v[214:215], s[60:61], 0, v[144:145]
	s_add_i32 m0, s39, 0x2000
	s_nop 0
	global_load_lds_dwordx4 v[214:215], off
	v_lshl_add_u64 v[214:215], v[244:245], 0, s[76:77]
	s_mov_b32 m0, s27
	s_nop 0
	global_load_lds_dwordx4 v[214:215], off
	v_lshl_add_u64 v[214:215], v[246:247], 0, s[76:77]
	s_mov_b32 m0, s28
	s_nop 0
	global_load_lds_dwordx4 v[214:215], off
	s_waitcnt vmcnt(8)
	s_waitcnt lgkmcnt(0)
	v_mfma_f32_16x16x32_bf16 v[94:97], v[78:81], v[182:185], v[94:97]
	v_mfma_f32_16x16x32_bf16 v[90:93], v[158:161], v[182:185], v[90:93]
	v_mfma_f32_16x16x32_bf16 v[86:89], v[78:81], v[190:193], v[86:89]
	v_mfma_f32_16x16x32_bf16 v[82:85], v[158:161], v[190:193], v[82:85]
	v_mfma_f32_16x16x32_bf16 v[34:37], v[78:81], v[198:201], v[34:37]
	v_mfma_f32_16x16x32_bf16 v[6:9], v[158:161], v[198:201], v[6:9]
	v_mfma_f32_16x16x32_bf16 v[42:45], v[78:81], v[206:209], v[42:45]
	v_mfma_f32_16x16x32_bf16 v[10:13], v[158:161], v[206:209], v[10:13]
	s_barrier
	s_setprio 1
	s_waitcnt lgkmcnt(0)
	v_mfma_f32_16x16x32_bf16 v[94:97], v[134:137], v[186:189], v[94:97]
	v_mfma_f32_16x16x32_bf16 v[90:93], v[162:165], v[186:189], v[90:93]
	v_mfma_f32_16x16x32_bf16 v[86:89], v[134:137], v[194:197], v[86:89]
	v_mfma_f32_16x16x32_bf16 v[82:85], v[162:165], v[194:197], v[82:85]
	v_mfma_f32_16x16x32_bf16 v[34:37], v[134:137], v[202:205], v[34:37]
	v_mfma_f32_16x16x32_bf16 v[6:9], v[162:165], v[202:205], v[6:9]
	v_mfma_f32_16x16x32_bf16 v[42:45], v[134:137], v[210:213], v[42:45]
	v_mfma_f32_16x16x32_bf16 v[10:13], v[162:165], v[210:213], v[10:13]
	s_setprio 0
	s_setprio 1
	v_mfma_f32_16x16x32_bf16 v[54:57], v[166:169], v[182:185], v[54:57]
	v_mfma_f32_16x16x32_bf16 v[78:81], v[170:173], v[186:189], v[54:57]
	v_mfma_f32_16x16x32_bf16 v[54:57], v[174:177], v[182:185], v[74:77]
	v_mfma_f32_16x16x32_bf16 v[74:77], v[178:181], v[186:189], v[54:57]
	v_mfma_f32_16x16x32_bf16 v[54:57], v[166:169], v[190:193], v[70:73]
	v_mfma_f32_16x16x32_bf16 v[70:73], v[170:173], v[194:197], v[54:57]
	v_mfma_f32_16x16x32_bf16 v[54:57], v[174:177], v[190:193], v[66:69]
	v_mfma_f32_16x16x32_bf16 v[38:41], v[166:169], v[198:201], v[38:41]
	v_mfma_f32_16x16x32_bf16 v[2:5], v[174:177], v[198:201], v[2:5]
	v_mfma_f32_16x16x32_bf16 v[46:49], v[166:169], v[206:209], v[46:49]
	v_mfma_f32_16x16x32_bf16 v[14:17], v[174:177], v[206:209], v[14:17]
	v_mfma_f32_16x16x32_bf16 v[66:69], v[178:181], v[194:197], v[54:57]
	v_mfma_f32_16x16x32_bf16 v[38:41], v[170:173], v[202:205], v[38:41]
	v_mfma_f32_16x16x32_bf16 v[2:5], v[178:181], v[202:205], v[2:5]
	v_mfma_f32_16x16x32_bf16 v[46:49], v[170:173], v[210:213], v[46:49]
	v_mfma_f32_16x16x32_bf16 v[14:17], v[178:181], v[210:213], v[14:17]
	s_setprio 0
	s_barrier
	s_add_i32 s38, s38, 2
	s_add_u32 vcc_lo, vcc_lo, 0x100
	s_addc_u32 vcc_hi, vcc_hi, 0
	s_cmp_gt_u32 s38, 13
	s_mov_b64 s[60:61], s[0:1]
	s_cbranch_scc0 .LBB0_1180
	s_and_b64 vcc, exec, s[42:43]
	s_cbranch_vccz .LBB0_1183
	s_barrier

.LBB0_1459:
	ds_read_b128 v[96:99], v184
	ds_read_b128 v[100:103], v184 offset:1024
	ds_read_b128 v[104:107], v184 offset:2048
	ds_read_b128 v[108:111], v184 offset:3072
	ds_read_b128 v[158:161], v185
	ds_read_b128 v[162:165], v185 offset:1024
	ds_read_b128 v[166:169], v185 offset:2048
	ds_read_b128 v[170:173], v185 offset:3072
	s_add_u32 s4, s24, 0x100
	s_addc_u32 s5, s25, 0
	s_cmp_eq_u32 s50, 40
	s_cselect_b32 s29, s19, s5
	s_cselect_b32 s28, s18, s4
	s_cselect_b32 s27, s21, s49
	s_cselect_b32 s26, s20, s23
	v_lshl_add_u64 v[178:179], s[24:25], 0, v[150:151]
	s_add_i32 m0, s34, 0xc000
	ds_read_b128 v[174:177], v186
	ds_read_b128 v[190:193], v186 offset:1024
	ds_read_b128 v[194:197], v186 offset:2048
	ds_read_b128 v[198:201], v186 offset:3072
	ds_read_b128 v[202:205], v186 offset:4096
	ds_read_b128 v[206:209], v186 offset:5120
	ds_read_b128 v[210:213], v186 offset:6144
	ds_read_b128 v[214:217], v186 offset:7168
	global_load_lds_dwordx4 v[178:179], off
	v_lshl_add_u64 v[178:179], s[24:25], 0, v[152:153]
	s_add_i32 m0, s34, 0xe000
	s_nop 0
	global_load_lds_dwordx4 v[178:179], off
	s_waitcnt vmcnt(8)
	s_waitcnt lgkmcnt(0)
	v_mfma_f32_16x16x32_bf16 v[140:143], v[96:99], v[174:177], v[140:143]
	v_mfma_f32_16x16x32_bf16 v[136:139], v[104:107], v[174:177], v[136:139]
	v_mfma_f32_16x16x32_bf16 v[124:127], v[96:99], v[194:197], v[124:127]
	v_mfma_f32_16x16x32_bf16 v[120:123], v[104:107], v[194:197], v[120:123]
	v_mfma_f32_16x16x32_bf16 v[92:95], v[96:99], v[202:205], v[92:95]
	v_mfma_f32_16x16x32_bf16 v[88:91], v[104:107], v[202:205], v[88:91]
	v_mfma_f32_16x16x32_bf16 v[76:79], v[96:99], v[210:213], v[76:79]
	v_mfma_f32_16x16x32_bf16 v[72:75], v[104:107], v[210:213], v[72:75]
	s_barrier
	s_setprio 1
	s_waitcnt lgkmcnt(0)
	v_mfma_f32_16x16x32_bf16 v[140:143], v[100:103], v[190:193], v[140:143]
	v_mfma_f32_16x16x32_bf16 v[136:139], v[108:111], v[190:193], v[136:139]
	v_mfma_f32_16x16x32_bf16 v[124:127], v[100:103], v[198:201], v[124:127]
	v_mfma_f32_16x16x32_bf16 v[120:123], v[108:111], v[198:201], v[120:123]
	v_mfma_f32_16x16x32_bf16 v[92:95], v[100:103], v[206:209], v[92:95]
	v_mfma_f32_16x16x32_bf16 v[88:91], v[108:111], v[206:209], v[88:91]
	v_mfma_f32_16x16x32_bf16 v[76:79], v[100:103], v[214:217], v[76:79]
	v_mfma_f32_16x16x32_bf16 v[72:75], v[108:111], v[214:217], v[72:75]
	s_setprio 0
	s_setprio 1
	v_mfma_f32_16x16x32_bf16 v[132:135], v[158:161], v[174:177], v[132:135]
	v_mfma_f32_16x16x32_bf16 v[128:131], v[166:169], v[174:177], v[128:131]
	v_mfma_f32_16x16x32_bf16 v[116:119], v[158:161], v[194:197], v[116:119]
	v_mfma_f32_16x16x32_bf16 v[112:115], v[166:169], v[194:197], v[112:115]
	v_mfma_f32_16x16x32_bf16 v[84:87], v[158:161], v[202:205], v[84:87]
	v_mfma_f32_16x16x32_bf16 v[80:83], v[166:169], v[202:205], v[80:83]
	v_mfma_f32_16x16x32_bf16 v[68:71], v[158:161], v[210:213], v[68:71]
	v_mfma_f32_16x16x32_bf16 v[64:67], v[166:169], v[210:213], v[64:67]
	v_mfma_f32_16x16x32_bf16 v[132:135], v[162:165], v[190:193], v[132:135]
	v_mfma_f32_16x16x32_bf16 v[128:131], v[170:173], v[190:193], v[128:131]
	v_mfma_f32_16x16x32_bf16 v[116:119], v[162:165], v[198:201], v[116:119]
	v_mfma_f32_16x16x32_bf16 v[112:115], v[170:173], v[198:201], v[112:115]
	v_mfma_f32_16x16x32_bf16 v[84:87], v[162:165], v[206:209], v[84:87]
	v_mfma_f32_16x16x32_bf16 v[80:83], v[170:173], v[206:209], v[80:83]
	v_mfma_f32_16x16x32_bf16 v[68:71], v[162:165], v[214:217], v[68:71]
	v_mfma_f32_16x16x32_bf16 v[64:67], v[170:173], v[214:217], v[64:67]
	s_setprio 0
	s_barrier
	s_add_i32 s24, s43, s33
	v_lshl_add_u64 v[178:179], s[26:27], 0, v[144:145]
	s_mov_b32 m0, s24
	ds_read_b128 v[174:177], v186 offset:16384
	ds_read_b128 v[190:193], v186 offset:17408
	ds_read_b128 v[194:197], v186 offset:18432
	ds_read_b128 v[198:201], v186 offset:19456
	ds_read_b128 v[202:205], v186 offset:20480
	ds_read_b128 v[206:209], v186 offset:21504
	ds_read_b128 v[210:213], v186 offset:22528
	ds_read_b128 v[214:217], v186 offset:23552
	global_load_lds_dwordx4 v[178:179], off
	s_add_i32 m0, s24, 0x2000
	s_add_u32 s24, s26, 0xb0000
	v_lshl_add_u64 v[220:221], s[26:27], 0, v[146:147]
	s_addc_u32 s25, s27, 0
	s_add_i32 s51, s44, s33
	global_load_lds_dwordx4 v[220:221], off
	v_lshl_add_u64 v[222:223], s[24:25], 0, v[144:145]
	s_mov_b32 m0, s51
	v_lshl_add_u64 v[224:225], s[28:29], 0, v[146:147]
	global_load_lds_dwordx4 v[222:223], off
	v_lshl_add_u64 v[222:223], s[24:25], 0, v[146:147]
	s_add_i32 m0, s51, 0x2000
	s_nop 0
	global_load_lds_dwordx4 v[222:223], off
	v_lshl_add_u64 v[222:223], s[28:29], 0, v[144:145]
	s_mov_b32 m0, s34
	s_nop 0
	global_load_lds_dwordx4 v[222:223], off
	s_mov_b32 m0, s35
	s_nop 0
	global_load_lds_dwordx4 v[224:225], off
	s_waitcnt vmcnt(8)
	s_waitcnt lgkmcnt(0)
	v_mfma_f32_16x16x32_bf16 v[60:63], v[96:99], v[174:177], v[60:63]
	v_mfma_f32_16x16x32_bf16 v[56:59], v[104:107], v[174:177], v[56:59]
	v_mfma_f32_16x16x32_bf16 v[44:47], v[96:99], v[194:197], v[44:47]
	v_mfma_f32_16x16x32_bf16 v[40:43], v[104:107], v[194:197], v[40:43]
	v_mfma_f32_16x16x32_bf16 v[28:31], v[96:99], v[202:205], v[28:31]
	v_mfma_f32_16x16x32_bf16 v[24:27], v[104:107], v[202:205], v[24:27]
	v_mfma_f32_16x16x32_bf16 v[12:15], v[96:99], v[210:213], v[12:15]
	v_mfma_f32_16x16x32_bf16 v[8:11], v[104:107], v[210:213], v[8:11]
	s_barrier
	s_setprio 1
	s_waitcnt lgkmcnt(0)
	v_mfma_f32_16x16x32_bf16 v[60:63], v[100:103], v[190:193], v[60:63]
	v_mfma_f32_16x16x32_bf16 v[56:59], v[108:111], v[190:193], v[56:59]
	v_mfma_f32_16x16x32_bf16 v[44:47], v[100:103], v[198:201], v[44:47]
	v_mfma_f32_16x16x32_bf16 v[40:43], v[108:111], v[198:201], v[40:43]
	v_mfma_f32_16x16x32_bf16 v[28:31], v[100:103], v[206:209], v[28:31]
	v_mfma_f32_16x16x32_bf16 v[24:27], v[108:111], v[206:209], v[24:27]
	v_mfma_f32_16x16x32_bf16 v[12:15], v[100:103], v[214:217], v[12:15]
	v_mfma_f32_16x16x32_bf16 v[8:11], v[108:111], v[214:217], v[8:11]
	s_setprio 0
	s_setprio 1
	v_mfma_f32_16x16x32_bf16 v[52:55], v[158:161], v[174:177], v[52:55]
	v_mfma_f32_16x16x32_bf16 v[48:51], v[166:169], v[174:177], v[48:51]
	v_mfma_f32_16x16x32_bf16 v[36:39], v[158:161], v[194:197], v[36:39]
	v_mfma_f32_16x16x32_bf16 v[32:35], v[166:169], v[194:197], v[32:35]
	v_mfma_f32_16x16x32_bf16 v[20:23], v[158:161], v[202:205], v[20:23]
	v_mfma_f32_16x16x32_bf16 v[16:19], v[166:169], v[202:205], v[16:19]
	v_mfma_f32_16x16x32_bf16 v[4:7], v[158:161], v[210:213], v[4:7]
	v_mfma_f32_16x16x32_bf16 v[0:3], v[166:169], v[210:213], v[0:3]
	v_mfma_f32_16x16x32_bf16 v[52:55], v[162:165], v[190:193], v[52:55]
	v_mfma_f32_16x16x32_bf16 v[48:51], v[170:173], v[190:193], v[48:51]
	v_mfma_f32_16x16x32_bf16 v[36:39], v[162:165], v[198:201], v[36:39]
	v_mfma_f32_16x16x32_bf16 v[32:35], v[170:173], v[198:201], v[32:35]
	v_mfma_f32_16x16x32_bf16 v[20:23], v[162:165], v[206:209], v[20:23]
	v_mfma_f32_16x16x32_bf16 v[16:19], v[170:173], v[206:209], v[16:19]
	v_mfma_f32_16x16x32_bf16 v[4:7], v[162:165], v[214:217], v[4:7]
	v_mfma_f32_16x16x32_bf16 v[0:3], v[170:173], v[214:217], v[0:3]
	s_setprio 0
	s_barrier
	s_add_i32 s51, 0, 0x18000
	s_add_i32 s52, 0, 0x1c000
	v_add_u32_e32 v108, s51, v181
	v_add_u32_e32 v170, s52, v181
	ds_read_b128 v[96:99], v108
	ds_read_b128 v[100:103], v108 offset:1024
	ds_read_b128 v[104:107], v108 offset:2048
	ds_read_b128 v[108:111], v108 offset:3072
	ds_read_b128 v[158:161], v170
	ds_read_b128 v[162:165], v170 offset:1024
	ds_read_b128 v[166:169], v170 offset:2048
	ds_read_b128 v[170:173], v170 offset:3072
	s_add_u32 s24, s28, 0xb0000
	s_addc_u32 s25, s29, 0
	s_mov_b32 m0, s36
	v_lshl_add_u64 v[226:227], s[24:25], 0, v[144:145]
	ds_read_b128 v[174:177], v186 offset:32768
	ds_read_b128 v[190:193], v186 offset:33792
	ds_read_b128 v[194:197], v186 offset:34816
	ds_read_b128 v[198:201], v186 offset:35840
	ds_read_b128 v[202:205], v186 offset:36864
	ds_read_b128 v[206:209], v186 offset:37888
	ds_read_b128 v[210:213], v186 offset:38912
	ds_read_b128 v[214:217], v186 offset:39936
	global_load_lds_dwordx4 v[226:227], off
	v_lshl_add_u64 v[226:227], s[24:25], 0, v[146:147]
	s_mov_b32 m0, s37
	s_nop 0
	global_load_lds_dwordx4 v[226:227], off
	s_waitcnt vmcnt(8)
	s_waitcnt lgkmcnt(0)
	v_mfma_f32_16x16x32_bf16 v[140:143], v[96:99], v[174:177], v[140:143]
	v_mfma_f32_16x16x32_bf16 v[136:139], v[104:107], v[174:177], v[136:139]
	v_mfma_f32_16x16x32_bf16 v[124:127], v[96:99], v[194:197], v[124:127]
	v_mfma_f32_16x16x32_bf16 v[120:123], v[104:107], v[194:197], v[120:123]
	v_mfma_f32_16x16x32_bf16 v[92:95], v[96:99], v[202:205], v[92:95]
	v_mfma_f32_16x16x32_bf16 v[88:91], v[104:107], v[202:205], v[88:91]
	v_mfma_f32_16x16x32_bf16 v[76:79], v[96:99], v[210:213], v[76:79]
	v_mfma_f32_16x16x32_bf16 v[72:75], v[104:107], v[210:213], v[72:75]
	s_barrier
	s_setprio 1
	s_waitcnt lgkmcnt(0)
	v_mfma_f32_16x16x32_bf16 v[140:143], v[100:103], v[190:193], v[140:143]
	v_mfma_f32_16x16x32_bf16 v[136:139], v[108:111], v[190:193], v[136:139]
	v_mfma_f32_16x16x32_bf16 v[124:127], v[100:103], v[198:201], v[124:127]
	v_mfma_f32_16x16x32_bf16 v[120:123], v[108:111], v[198:201], v[120:123]
	v_mfma_f32_16x16x32_bf16 v[92:95], v[100:103], v[206:209], v[92:95]
	v_mfma_f32_16x16x32_bf16 v[88:91], v[108:111], v[206:209], v[88:91]
	v_mfma_f32_16x16x32_bf16 v[76:79], v[100:103], v[214:217], v[76:79]
	v_mfma_f32_16x16x32_bf16 v[72:75], v[108:111], v[214:217], v[72:75]
	s_setprio 0
	s_setprio 1
	v_mfma_f32_16x16x32_bf16 v[132:135], v[158:161], v[174:177], v[132:135]
	v_mfma_f32_16x16x32_bf16 v[128:131], v[166:169], v[174:177], v[128:131]
	v_mfma_f32_16x16x32_bf16 v[116:119], v[158:161], v[194:197], v[116:119]
	v_mfma_f32_16x16x32_bf16 v[112:115], v[166:169], v[194:197], v[112:115]
	v_mfma_f32_16x16x32_bf16 v[84:87], v[158:161], v[202:205], v[84:87]
	v_mfma_f32_16x16x32_bf16 v[80:83], v[166:169], v[202:205], v[80:83]
	v_mfma_f32_16x16x32_bf16 v[68:71], v[158:161], v[210:213], v[68:71]
	v_mfma_f32_16x16x32_bf16 v[64:67], v[166:169], v[210:213], v[64:67]
	v_mfma_f32_16x16x32_bf16 v[132:135], v[162:165], v[190:193], v[132:135]
	v_mfma_f32_16x16x32_bf16 v[128:131], v[170:173], v[190:193], v[128:131]
	v_mfma_f32_16x16x32_bf16 v[116:119], v[162:165], v[198:201], v[116:119]
	v_mfma_f32_16x16x32_bf16 v[112:115], v[170:173], v[198:201], v[112:115]
	v_mfma_f32_16x16x32_bf16 v[84:87], v[162:165], v[206:209], v[84:87]
	v_mfma_f32_16x16x32_bf16 v[80:83], v[170:173], v[206:209], v[80:83]
	v_mfma_f32_16x16x32_bf16 v[68:71], v[162:165], v[214:217], v[68:71]
	v_mfma_f32_16x16x32_bf16 v[64:67], v[170:173], v[214:217], v[64:67]
	s_setprio 0
	s_barrier
	s_add_i32 s24, s51, s33
	v_lshl_add_u64 v[178:179], v[178:179], 0, s[12:13]
	s_mov_b32 m0, s24
	ds_read_b128 v[174:177], v186 offset:49152
	ds_read_b128 v[190:193], v186 offset:50176
	ds_read_b128 v[194:197], v186 offset:51200
	ds_read_b128 v[198:201], v186 offset:52224
	ds_read_b128 v[202:205], v186 offset:53248
	ds_read_b128 v[206:209], v186 offset:54272
	ds_read_b128 v[210:213], v186 offset:55296
	ds_read_b128 v[214:217], v186 offset:56320
	global_load_lds_dwordx4 v[178:179], off
	s_add_i32 m0, s24, 0x2000
	s_add_u32 s24, s26, 0xb0080
	v_lshl_add_u64 v[178:179], v[220:221], 0, s[12:13]
	s_addc_u32 s25, s27, 0
	s_add_i32 s26, s52, s33
	global_load_lds_dwordx4 v[178:179], off
	v_lshl_add_u64 v[178:179], s[24:25], 0, v[144:145]
	s_mov_b32 m0, s26
	s_nop 0
	global_load_lds_dwordx4 v[178:179], off
	v_lshl_add_u64 v[178:179], s[24:25], 0, v[146:147]
	s_add_i32 m0, s26, 0x2000
	s_nop 0
	global_load_lds_dwordx4 v[178:179], off
	v_lshl_add_u64 v[178:179], v[222:223], 0, s[12:13]
	s_mov_b32 m0, s40
	s_nop 0
	global_load_lds_dwordx4 v[178:179], off
	v_lshl_add_u64 v[178:179], v[224:225], 0, s[12:13]
	s_mov_b32 m0, s41
	s_nop 0
	global_load_lds_dwordx4 v[178:179], off
	s_waitcnt vmcnt(8)
	s_waitcnt lgkmcnt(0)
	v_mfma_f32_16x16x32_bf16 v[60:63], v[96:99], v[174:177], v[60:63]
	v_mfma_f32_16x16x32_bf16 v[56:59], v[104:107], v[174:177], v[56:59]
	v_mfma_f32_16x16x32_bf16 v[44:47], v[96:99], v[194:197], v[44:47]
	v_mfma_f32_16x16x32_bf16 v[40:43], v[104:107], v[194:197], v[40:43]
	v_mfma_f32_16x16x32_bf16 v[28:31], v[96:99], v[202:205], v[28:31]
	v_mfma_f32_16x16x32_bf16 v[24:27], v[104:107], v[202:205], v[24:27]
	v_mfma_f32_16x16x32_bf16 v[12:15], v[96:99], v[210:213], v[12:15]
	v_mfma_f32_16x16x32_bf16 v[8:11], v[104:107], v[210:213], v[8:11]
	s_barrier
	s_setprio 1
	s_waitcnt lgkmcnt(0)
	v_mfma_f32_16x16x32_bf16 v[60:63], v[100:103], v[190:193], v[60:63]
	v_mfma_f32_16x16x32_bf16 v[56:59], v[108:111], v[190:193], v[56:59]
	v_mfma_f32_16x16x32_bf16 v[44:47], v[100:103], v[198:201], v[44:47]
	v_mfma_f32_16x16x32_bf16 v[40:43], v[108:111], v[198:201], v[40:43]
	v_mfma_f32_16x16x32_bf16 v[28:31], v[100:103], v[206:209], v[28:31]
	v_mfma_f32_16x16x32_bf16 v[24:27], v[108:111], v[206:209], v[24:27]
	v_mfma_f32_16x16x32_bf16 v[12:15], v[100:103], v[214:217], v[12:15]
	v_mfma_f32_16x16x32_bf16 v[8:11], v[108:111], v[214:217], v[8:11]
	s_setprio 0
	s_setprio 1
	v_mfma_f32_16x16x32_bf16 v[52:55], v[158:161], v[174:177], v[52:55]
	v_mfma_f32_16x16x32_bf16 v[48:51], v[166:169], v[174:177], v[48:51]
	v_mfma_f32_16x16x32_bf16 v[36:39], v[158:161], v[194:197], v[36:39]
	v_mfma_f32_16x16x32_bf16 v[32:35], v[166:169], v[194:197], v[32:35]
	v_mfma_f32_16x16x32_bf16 v[20:23], v[158:161], v[202:205], v[20:23]
	v_mfma_f32_16x16x32_bf16 v[16:19], v[166:169], v[202:205], v[16:19]
	v_mfma_f32_16x16x32_bf16 v[4:7], v[158:161], v[210:213], v[4:7]
	v_mfma_f32_16x16x32_bf16 v[0:3], v[166:169], v[210:213], v[0:3]
	v_mfma_f32_16x16x32_bf16 v[52:55], v[162:165], v[190:193], v[52:55]
	v_mfma_f32_16x16x32_bf16 v[48:51], v[170:173], v[190:193], v[48:51]
	v_mfma_f32_16x16x32_bf16 v[36:39], v[162:165], v[198:201], v[36:39]
	v_mfma_f32_16x16x32_bf16 v[32:35], v[170:173], v[198:201], v[32:35]
	v_mfma_f32_16x16x32_bf16 v[20:23], v[162:165], v[206:209], v[20:23]
	v_mfma_f32_16x16x32_bf16 v[16:19], v[170:173], v[206:209], v[16:19]
	v_mfma_f32_16x16x32_bf16 v[4:7], v[162:165], v[214:217], v[4:7]
	v_mfma_f32_16x16x32_bf16 v[0:3], v[170:173], v[214:217], v[0:3]
	s_setprio 0
	s_barrier
	s_add_i32 s50, s50, 2
	s_add_u32 s23, s23, 0x100
	s_addc_u32 s49, s49, 0
	s_cmp_gt_u32 s50, 41
	s_mov_b64 s[24:25], s[4:5]
	s_cbranch_scc0 .LBB0_1459
	s_and_b64 vcc, exec, s[14:15]
	s_cbranch_vccz .LBB0_1462
	s_barrier
